# attention: padded T5 bias table in LDS (near-diagonal tiles use 8 ds_read2 lookups, no clamp VALU), far path and no-rescale path made fall-through
# baseline (speedup 1.0000x reference)
; DI void phase_attn(int wid0, const Params& p, int L, unsigned char* lds, bool dry) {
;     ...
;         const int qrow0 = meta ? MREG : b * 4096 + 128 * qb, qpos0 = meta ? 0 : 16 + 128 * qb, ntiles = meta ? 1 : 1 + 4 * (qb + 1);
;         if (tid < 130) tab[tid] = (tid < 129) ? biasT[hh * 129 + tid] : -__builtin_inff();
;         int myrow = qrow0 + 32 * rg + r32; if (meta && myrow > MREG + 63) myrow = MREG + 63;
;         const bf16_t* qp = qbuf + (size_t)myrow * 2048 + hh * 256 + psub * 128 + hi * 8;
;         unsigned char* qlds = lds + wid * 8192 + lane * 16;
; #pragma unroll
;         for (int d0 = 0; d0 < 8; ++d0) *(bf16x8*)(qlds + d0 * 1024) = *(const bf16x8*)(qp + d0 * 16);
;         const int wq0 = qpos0 + 32 * rg, qpos = wq0 + r32;
;         const float bfar = biasT[hh * 129 + 128];
;         const bf16_t* kh_ = kbuf + hh * 256; const bf16_t* vh_ = vbuf + hh * 256;
;         attn_stage(kh_ + (size_t)MREG * 2048, vh_ + (size_t)MREG * 2048, koff, voff, ldsl + 65536, wid);
.LBB0_97:
	s_or_b64 exec, exec, s[10:11]
	v_subrev_u32_e32 v2, s37, v191
	v_lshrrev_b32_e32 v2, 2, v2
	v_cmp_gt_u32_e32 vcc, 0xfc, v2
	s_mov_b64 s[10:11], vcc
	v_cmp_gt_u32_e32 vcc, 62, v2
	v_add_u32_e32 v2, 0xffffffc2, v2
	v_max_i32_e32 v2, 0, v2
	v_min_i32_e32 v2, 0x80, v2
	v_add_u32_e32 v2, s8, v2
	v_mov_b32_e32 v3, 0
	v_readlane_b32 s6, v245, 40
	v_readlane_b32 s7, v245, 41
	s_mov_b64 s[12:13], exec
	s_nop 1
	v_lshl_add_u64 v[2:3], v[2:3], 2, s[6:7]
	s_and_b64 exec, exec, s[10:11]
	global_load_dword v0, v[2:3], off
	v_mov_b32_e32 v3, 0xff800000
	s_waitcnt vmcnt(0)
	v_cndmask_b32_e32 v0, v0, v3, vcc
	ds_write_b32 v191, v0 offset:3328
	s_mov_b64 exec, s[12:13]
	s_lshl_b32 s40, s73, 12
	s_lshl_b32 s10, s75, 7
	s_add_i32 s9, s40, s10
	s_and_b64 s[6:7], s[76:77], exec
	s_cselect_b32 s71, 0x8000, s9
	s_lshl_b32 s6, s75, 2
	s_add_i32 s9, s6, 5
	s_and_b64 s[6:7], s[76:77], exec
	v_ashrrev_i32_e32 v0, 4, v4
	v_readlane_b32 s7, v245, 61
	v_and_b32_e32 v2, 15, v4
	v_lshrrev_b32_e32 v3, 1, v4
	v_add_u32_e32 v0, s7, v0
	v_bitop3_b32 v2, v0, v2, 15 bitop3:0x6c
	v_lshlrev_b32_e32 v0, 12, v0
	v_lshl_or_b32 v0, v2, 4, v0
	v_lshrrev_b32_e32 v2, 2, v4
	v_and_b32_e32 v3, 8, v3
	v_readlane_b32 s7, v245, 63
	v_and_or_b32 v2, v2, 3, v3
	v_lshlrev_b32_e32 v8, 3, v4
	v_add_u32_e32 v3, s7, v4
	v_readlane_b32 s7, v244, 1
	v_and_b32_e32 v7, 31, v4
	v_and_b32_e32 v3, 0xe0, v3
	v_and_b32_e32 v5, 24, v8
	v_lshl_add_u32 v2, v2, 11, s7
	v_or3_b32 v2, v2, v3, v5
	v_or_b32_e32 v3, s41, v7
	v_or_b32_e32 v3, s71, v3
	v_min_i32_e32 v9, 0x803f, v3
	v_cndmask_b32_e64 v10, v3, v9, s[76:77]
	s_cselect_b32 s6, 1, s9
	v_ashrrev_i32_e32 v11, 31, v10
	s_lshl_b32 s12, s49, 8
	v_lshlrev_b64 v[10:11], 12, v[10:11]
	s_ashr_i32 s13, s12, 31
	v_ashrrev_i32_e32 v6, 5, v4
	v_lshl_add_u64 v[10:11], s[0:1], 0, v[10:11]
	s_lshl_b64 s[78:79], s[12:13], 1
	v_readlane_b32 s12, v244, 5
	v_lshl_add_u64 v[10:11], v[10:11], 0, s[78:79]
	v_readlane_b32 s13, v244, 6
	v_lshlrev_b32_e32 v12, 3, v6
	v_ashrrev_i32_e32 v13, 31, v12
	v_lshl_add_u64 v[10:11], s[12:13], 1, v[10:11]
	v_lshl_add_u64 v[14:15], v[12:13], 1, v[10:11]
	global_load_dwordx4 v[248:251], v[14:15], off
	s_ashr_i32 s9, s8, 31
	s_lshl_b64 s[8:9], s[8:9], 2
	v_readlane_b32 s12, v245, 40
	v_lshlrev_b32_e32 v9, 4, v4
	v_readlane_b32 s7, v244, 7
	v_readlane_b32 s13, v245, 41
	s_add_u32 s8, s12, s8
	s_addc_u32 s9, s13, s9
	global_load_dword v176, v1, s[8:9] offset:512
	s_add_u32 s12, s28, s78
	s_addc_u32 s13, s29, s79
	s_mov_b64 s[84:85], s[12:13]
	v_readlane_b32 s8, v245, 38
	v_readlane_b32 s9, v245, 39
	s_add_u32 s8, s8, s78
	v_readlane_b32 s7, v244, 9
	s_addc_u32 s9, s9, s79
	s_mov_b64 s[86:87], s[8:9]
	v_lshl_add_u64 v[178:179], s[12:13], 0, v[0:1]
	v_mov_b32_e32 v131, v0
	s_mov_b64 s[14:15], 0x8000000
	s_add_i32 s7, s7, 0
	v_lshlrev_b32_e32 v2, 1, v2
	s_add_i32 m0, s7, 0x10000
	s_mov_b64 s[12:13], 0x8000100
	v_mov_b32_e32 v3, v1
	v_lshl_add_u64 v[180:181], s[8:9], 0, v[2:3]
	v_mov_b32_e32 v208, v2
	v_lshl_add_u64 v[2:3], v[180:181], 0, s[14:15]
	s_mov_b64 s[8:9], 0x8010000
	global_load_dwordx4 v[252:255], v[14:15], off offset:32
	global_load_dwordx4 v[200:203], v[14:15], off offset:64
	global_load_dwordx4 v[204:207], v[14:15], off offset:96
	global_load_dwordx4 v[164:167], v[14:15], off offset:128
	global_load_dwordx4 v[168:171], v[14:15], off offset:160
	global_load_dwordx4 v[172:175], v[14:15], off offset:192
	global_load_dwordx4 v[232:235], v[14:15], off offset:224
	v_lshl_add_u64 v[10:11], v[178:179], 0, s[14:15]
	global_load_lds_dwordx4 v[10:11], off
	v_lshl_add_u64 v[10:11], v[178:179], 0, s[12:13]
	s_add_i32 m0, s7, 0x12000
	s_nop 0
	global_load_lds_dwordx4 v[10:11], off
	s_add_i32 m0, s7, 0x0
	s_nop 0
	global_load_lds_dwordx4 v[2:3], off
	v_lshl_add_u64 v[2:3], v[180:181], 0, s[8:9]
	s_add_i32 m0, s7, 0x2000
	s_mov_b32 s7, 0
	global_load_lds_dwordx4 v[2:3], off
	s_cmp_lt_i32 s6, 1
	s_cbranch_scc1 .LBB0_114
; #define MFMA32(a, b, c) __builtin_amdgcn_mfma_f32_32x32x16_bf16((a), (b), (c), 0, 0, 0)
; DI void phase_attn(int wid0, const Params& p, int L, unsigned char* lds, bool dry) {
;     ...
;         f32x16 o[8];
; #pragma unroll
;         for (int d = 0; d < 8; ++d)
; #pragma unroll
;             for (int r = 0; r < 16; ++r) o[d][r] = 0.f;
;         float m_reg = -1e30f, l_reg = 0.f;
;         for (int t = 0; t < ntiles; ++t) {
;             asm volatile("s_waitcnt vmcnt(0) lgkmcnt(0)" ::: "memory"); __builtin_amdgcn_s_barrier(); asm volatile("" ::: "memory");
;             if (t + 1 < ntiles) attn_stage(kh_ + (size_t)(b * 4096 + 32 * t) * 2048, vh_ + (size_t)(b * 4096 + 32 * t) * 2048, koff, voff, ldsl + 65536 + ((t + 1) & 1) * 32768, wid);
;             const int kpos0 = (t == 0) ? 0 : 16 + 32 * (t - 1);
;             if (kpos0 <= wq0 + 31) {
;                 const unsigned char* Ks = lds + 65536 + (t & 1) * 32768 + psub * 8192;
;                 f32x16 p0, p0b;
; #pragma unroll
;                 for (int r = 0; r < 16; ++r) { p0[r] = 0.f; p0b[r] = 0.f; }
;                 int swz = (r32 & 6) << 4, kro = r32 * 256 + ((hi ^ (r32 & 1)) << 4); asm volatile("" : "+v"(swz), "+v"(kro));
; #pragma unroll
;                 for (int d0 = 0; d0 < 8; d0 += 2) {
;                     const bf16x8 b0 = *(const bf16x8*)(Ks + kro + ((d0 * 32) ^ swz));
;                     const bf16x8 qf = *(const bf16x8*)(qlds + d0 * 1024);
;                     const bf16x8 b1 = *(const bf16x8*)(Ks + kro + (((d0 + 1) * 32) ^ swz));
;                     const bf16x8 qg = *(const bf16x8*)(qlds + (d0 + 1) * 1024);
;                     p0 = MFMA32(b0, qf, p0);
;                     p0b = MFMA32(b1, qg, p0b);
;                     if (d0 == 2) __builtin_amdgcn_sched_barrier(0);
;                 }
; #pragma unroll
;                 for (int r = 0; r < 16; ++r) p0[r] += p0b[r];
;                 __builtin_amdgcn_sched_barrier(0);
;                 if (t > 0 && wq0 - (kpos0 + 31) >= 128) {
	s_or_b32 s10, s10, 16
	v_lshlrev_b32_e32 v0, 8, v7
	v_bitop3_b32 v2, v6, v4, 1 bitop3:0x78
	s_and_b64 s[8:9], s[76:77], exec
	v_lshl_add_u32 v193, v2, 4, v0
	v_lshlrev_b32_e32 v2, 1, v4
	s_cselect_b32 s39, 0, s10
	v_and_b32_e32 v0, 0xc0, v9
	v_and_b32_e32 v2, 32, v2
	v_readlane_b32 s48, v244, 17
	s_or_b32 s8, s39, s41
	v_and_b32_e32 v3, 0x100, v8
	v_add3_u32 v0, s48, v0, v2
	v_mov_b32_e32 v14, v1
	v_mov_b32_e32 v15, v1
	s_add_i32 s38, s8, 31
	v_and_b32_e32 v192, 0xe0, v9
	v_lshlrev_b32_e32 v194, 2, v6
	v_add_u32_e32 v195, s8, v7
	v_cmp_gt_u32_e64 s[8:9], 32, v4
	v_lshl_add_u32 v196, v7, 2, s2
	v_lshlrev_b32_e32 v16, 4, v6
	v_cmp_gt_i32_e64 s[10:11], 4, v6
	v_cmp_gt_i32_e64 s[18:19], 2, v6
	v_cmp_gt_i32_e64 s[20:21], 0, v6
	v_cmp_gt_i32_e64 s[22:23], -2, v6
	v_add3_u32 v212, v0, v3, v5
	v_add_u32_e32 v212, 0xffff0000, v212
	v_mov_b32_e32 v0, v1
	v_mov_b32_e32 v2, v1
	v_mov_b32_e32 v3, v1
	v_mov_b32_e32 v4, v1
	v_mov_b32_e32 v5, v1
	v_mov_b32_e32 v6, v1
	v_mov_b32_e32 v7, v1
	v_mov_b32_e32 v8, v1
	v_mov_b32_e32 v9, v1
	v_mov_b32_e32 v10, v1
	v_mov_b32_e32 v11, v1
	v_mov_b32_e32 v12, v1
	v_mov_b32_e32 v13, v1
	v_mov_b64_e32 v[128:129], v[14:15]
	v_mov_b64_e32 v[112:113], v[14:15]
	v_mov_b64_e32 v[96:97], v[14:15]
	v_mov_b64_e32 v[80:81], v[14:15]
	v_mov_b64_e32 v[64:65], v[14:15]
	v_mov_b64_e32 v[48:49], v[14:15]
	v_mov_b64_e32 v[32:33], v[14:15]
	v_or_b32_e32 v197, 1, v194
	v_or_b32_e32 v198, 2, v194
	v_or_b32_e32 v199, 3, v194
	v_readlane_b32 s48, v244, 19
	v_add_u32_e32 v214, s2, v16
	v_mov_b64_e32 v[126:127], v[12:13]
	v_mov_b64_e32 v[124:125], v[10:11]
	v_mov_b64_e32 v[122:123], v[8:9]
	v_mov_b64_e32 v[120:121], v[6:7]
	v_mov_b64_e32 v[118:119], v[4:5]
	v_mov_b64_e32 v[116:117], v[2:3]
	v_mov_b64_e32 v[114:115], v[0:1]
	v_mov_b64_e32 v[110:111], v[12:13]
	v_mov_b64_e32 v[108:109], v[10:11]
	v_mov_b64_e32 v[106:107], v[8:9]
	v_mov_b64_e32 v[104:105], v[6:7]
	v_mov_b64_e32 v[102:103], v[4:5]
	v_mov_b64_e32 v[100:101], v[2:3]
	v_mov_b64_e32 v[98:99], v[0:1]
	v_mov_b64_e32 v[94:95], v[12:13]
	v_mov_b64_e32 v[92:93], v[10:11]
	v_mov_b64_e32 v[90:91], v[8:9]
	v_mov_b64_e32 v[88:89], v[6:7]
	v_mov_b64_e32 v[86:87], v[4:5]
	v_mov_b64_e32 v[84:85], v[2:3]
	v_mov_b64_e32 v[82:83], v[0:1]
	v_mov_b64_e32 v[78:79], v[12:13]
	v_mov_b64_e32 v[76:77], v[10:11]
	v_mov_b64_e32 v[74:75], v[8:9]
	v_mov_b64_e32 v[72:73], v[6:7]
	v_mov_b64_e32 v[70:71], v[4:5]
	v_mov_b64_e32 v[68:69], v[2:3]
	v_mov_b64_e32 v[66:67], v[0:1]
	v_mov_b64_e32 v[62:63], v[12:13]
	v_mov_b64_e32 v[60:61], v[10:11]
	v_mov_b64_e32 v[58:59], v[8:9]
	v_mov_b64_e32 v[56:57], v[6:7]
	v_mov_b64_e32 v[54:55], v[4:5]
	v_mov_b64_e32 v[52:53], v[2:3]
	v_mov_b64_e32 v[50:51], v[0:1]
	v_mov_b64_e32 v[46:47], v[12:13]
	v_mov_b64_e32 v[44:45], v[10:11]
	v_mov_b64_e32 v[42:43], v[8:9]
	v_mov_b64_e32 v[40:41], v[6:7]
	v_mov_b64_e32 v[38:39], v[4:5]
	v_mov_b64_e32 v[36:37], v[2:3]
	v_mov_b64_e32 v[34:35], v[0:1]
	v_mov_b64_e32 v[30:31], v[12:13]
	v_mov_b64_e32 v[28:29], v[10:11]
	v_mov_b64_e32 v[26:27], v[8:9]
	v_mov_b64_e32 v[24:25], v[6:7]
	v_mov_b64_e32 v[22:23], v[4:5]
	v_mov_b64_e32 v[20:21], v[2:3]
	v_mov_b64_e32 v[18:19], v[0:1]
	v_mov_b64_e32 v[16:17], v[14:15]
	v_cmp_gt_i32_e64 s[12:13], 16, v197
	v_cmp_gt_i32_e64 s[14:15], 16, v198
	v_cmp_gt_i32_e64 s[16:17], 16, v199
	s_waitcnt vmcnt(11)
	v_mov_b32_e32 v182, v176
	v_mov_b32_e32 v183, v176
	s_add_i32 s39, s48, s39
	v_mov_b32_e32 v130, 0
	v_mov_b32_e32 v213, 0xf149f2ca
	s_mov_b32 s66, 0
	s_mov_b32 s100, 0x100
	s_mov_b32 s67, 1
	s_mov_b32 s7, -16
	s_mov_b32 s97, 0x4138aa3b
	s_mov_b32 s80, s40
	s_mov_b32 s81, 0
	s_lshl_b64 s[80:81], s[80:81], 12
	s_add_u32 s88, s84, s80
	s_addc_u32 s89, s85, s81
	s_add_u32 s92, s86, s80
	s_addc_u32 s93, s87, s81
	s_add_u32 s94, s92, 0x10000
	s_addc_u32 s95, s93, 0
	s_add_u32 s90, s88, 0x100
	s_addc_u32 s91, s89, 0
	s_add_i32 s96, s4, 0xffff0000
	v_mov_b32_e32 v132, 0
	v_mov_b32_e32 v133, 0
	v_mov_b32_e32 v134, 0
	v_mov_b32_e32 v135, 0
	v_mov_b32_e32 v136, 0
	v_mov_b32_e32 v137, 0
	v_mov_b32_e32 v138, 0
	v_mov_b32_e32 v139, 0
	s_lshl_b32 s80, s96, 1
	s_add_i32 s80, s80, 0xc000
	v_lshl_add_u32 v226, v190, 4, s80
	ds_write_b128 v226, v[132:135]
	ds_write_b128 v226, v[132:135] offset:1024
	v_add_u32_e32 v226, s5, v193
	v_add_u32_e32 v188, v226, v192
	v_xad_u32 v177, v192, 32, v226
	v_xad_u32 v209, v192, 64, v226
	s_movk_i32 s80, 0x60
	v_xad_u32 v210, v192, s80, v226
	s_movk_i32 s80, 0x80
	v_xad_u32 v211, v192, s80, v226
	s_movk_i32 s80, 0xa0
	v_xad_u32 v215, v192, s80, v226
	s_movk_i32 s80, 0xc0
	v_xad_u32 v224, v192, s80, v226
	s_movk_i32 s80, 0xe0
	v_xad_u32 v225, v192, s80, v226
	v_mov_b64_e32 v[14:15], v[12:13]
	v_mov_b64_e32 v[12:13], v[10:11]
	v_mov_b64_e32 v[10:11], v[8:9]
	v_mov_b64_e32 v[8:9], v[6:7]
	v_mov_b64_e32 v[6:7], v[4:5]
	v_mov_b64_e32 v[4:5], v[2:3]
	v_mov_b64_e32 v[2:3], v[0:1]
	s_mov_b32 s69, 0
.LBB0_99:
	s_waitcnt vmcnt(0) lgkmcnt(0)
	s_barrier
	s_max_i32 s48, s7, 0
	s_cmp_gt_i32 s48, s38
	s_cbranch_scc1 .Lattn_skip0
	ds_read_b128 v[216:219], v188
	ds_read_b128 v[220:223], v177
	ds_read_b128 v[236:239], v209
	ds_read_b128 v[240:243], v210
	s_waitcnt lgkmcnt(2)
	v_mfma_f32_32x32x16_bf16 v[140:155], v[216:219], v[248:251], 0
	s_add_i32 m0, s4, 0x8000
	v_mfma_f32_32x32x16_bf16 v[140:155], v[220:223], v[252:255], v[140:155]
	global_load_lds_dwordx4 v131, s[88:89]
	ds_read_b128 v[216:219], v211
	ds_read_b128 v[220:223], v215
	s_waitcnt lgkmcnt(2)
	v_mfma_f32_32x32x16_bf16 v[140:155], v[236:239], v[200:203], v[140:155]
	s_add_i32 m0, s4, 0xa000
	v_mfma_f32_32x32x16_bf16 v[140:155], v[240:243], v[204:207], v[140:155]
	global_load_lds_dwordx4 v131, s[90:91]
	v_add_u32_e32 v131, 0x20000, v131
	ds_read_b128 v[236:239], v224
	ds_read_b128 v[240:243], v225
	s_waitcnt lgkmcnt(2)
	v_mfma_f32_32x32x16_bf16 v[140:155], v[216:219], v[164:167], v[140:155]
	s_add_i32 m0, s96, 0x4000
	v_mfma_f32_32x32x16_bf16 v[140:155], v[220:223], v[168:171], v[140:155]
	global_load_lds_dwordx4 v208, s[92:93]
	s_waitcnt lgkmcnt(0)
	v_mfma_f32_32x32x16_bf16 v[140:155], v[236:239], v[172:175], v[140:155]
	s_add_i32 m0, s96, 0x6000
	v_mfma_f32_32x32x16_bf16 v[140:155], v[240:243], v[232:235], v[140:155]
	global_load_lds_dwordx4 v208, s[94:95]
	v_add_u32_e32 v208, 0x20000, v208
	s_cmpk_gt_i32 s39, 0x7f
	s_cbranch_scc0 .Lattn_near0
	s_cmp_lg_u32 s67, 1
	s_cbranch_scc0 .Lattn_near0

; DI void phase_attn(int wid0, const Params& p, int L, unsigned char* lds, bool dry) {
;     ...
;                 float pmax = p0[0];
; #pragma unroll
;                 for (int r = 1; r < 16; ++r) pmax = fmaxf(pmax, p0[r]);
;                 { auto rr = __builtin_amdgcn_permlane32_swap(__float_as_uint(pmax), __float_as_uint(pmax), false, false); pmax = fmaxf(__uint_as_float(rr[0]), __uint_as_float(rr[1])); }
;                 float mn, alpha;
;                 if (__all(pmax - m_reg <= ATT_THR2)) { mn = m_reg; alpha = 1.f; }
;                 else { mn = fmaxf(m_reg, pmax); alpha = __builtin_amdgcn_exp2f(m_reg - mn); m_reg = mn; }
;                 float ps = 0.f;
; #pragma unroll
;                 for (int r = 0; r < 16; ++r) { p0[r] = __builtin_amdgcn_exp2f(p0[r] - mn); ps += p0[r]; }
;                 { auto rr = __builtin_amdgcn_permlane32_swap(__float_as_uint(ps), __float_as_uint(ps), false, false); ps = __uint_as_float(rr[0]) + __uint_as_float(rr[1]); }
;                 l_reg = l_reg * alpha + ps;
;                 __builtin_amdgcn_sched_barrier(0);
;                 bf16x8 pa0, pa1;
;     ...
;                 PK4(p0, 0, pa0); PK4(p0, 8, pa1);
;     ...
;                 __builtin_amdgcn_sched_barrier(0);
;                 if (__any(alpha < 1.f)) {
;                     if (hi == 0) al_l[r32] = alpha;
;                     asm volatile("s_waitcnt lgkmcnt(0)" ::: "memory");
;                     float ar[16];
; #pragma unroll
;                     for (int r = 0; r < 16; ++r) ar[r] = al_l[crow(r, hi)];
; #pragma unroll
;                     for (int d = 0; d < 8; ++d)
; #pragma unroll
;                         for (int r = 0; r < 16; ++r) o[d][r] *= ar[r];
;                 }
;                 __builtin_amdgcn_sched_barrier(0);
;                 LAS unsigned char* vbp = ldsl + 65536 + (t & 1) * 32768 + 16384 + v_rd_base(lane);
;                 __builtin_amdgcn_s_setprio(1);
;     ...
;                 {
;                     s16x4 a0, a1, a2, a3, b0_, b1_, b2_, b3_;
;                     PV_RD(0, a0, a1, a2, a3); SB();
;                     PV_RD(1, b0_, b1_, b2_, b3_); SB(); PV_MM(0, a0, a1, a2, a3); SB();
;                     PV_RD(2, a0, a1, a2, a3); SB(); PV_MM(1, b0_, b1_, b2_, b3_); SB();
;                     PV_RD(3, b0_, b1_, b2_, b3_); SB(); PV_MM(2, a0, a1, a2, a3); SB();
;                     PV_RD(4, a0, a1, a2, a3); SB(); PV_MM(3, b0_, b1_, b2_, b3_); SB();
.Lattn_region0:
	ds_read_b64_tr_b16 v[216:217], v212 offset:49152
	ds_read_b64_tr_b16 v[218:219], v212 offset:53248
	ds_read_b64_tr_b16 v[220:221], v212 offset:57344
	ds_read_b64_tr_b16 v[222:223], v212 offset:61440
	ds_read_b64_tr_b16 v[236:237], v212 offset:49664
	ds_read_b64_tr_b16 v[238:239], v212 offset:53760
	ds_read_b64_tr_b16 v[240:241], v212 offset:57856
	ds_read_b64_tr_b16 v[242:243], v212 offset:61952
	v_max3_f32 v226, v140, v141, v142
	v_max3_f32 v226, v226, v143, v144
	v_max3_f32 v226, v226, v145, v146
	v_max3_f32 v226, v226, v147, v148
	v_max3_f32 v226, v226, v149, v150
	v_max3_f32 v226, v226, v151, v152
	v_max3_f32 v226, v226, v153, v154
	v_max_f32_e32 v226, v226, v155
	v_mov_b32_e32 v227, v226
	s_nop 1
	v_permlane32_swap_b32_e32 v226, v227
	v_max_f32_e32 v226, v226, v227
	v_fma_f32 v226, v226, s82, v231
	v_sub_f32_e32 v227, v226, v213
	v_cmp_ge_f32_e32 vcc, s97, v227
	s_cmp_eq_u64 vcc, exec
	v_max_f32_e32 v226, v213, v226
	s_cselect_b64 vcc, -1, 0
	v_sub_f32_e32 v227, v213, v226
	v_cndmask_b32_e32 v213, v226, v213, vcc
	v_sub_f32_e32 v230, v231, v213
	s_waitcnt lgkmcnt(4)
	v_mfma_f32_32x32x16_bf16 v[114:129], v[132:135], v[216:219], v[114:129]
	v_mfma_f32_32x32x16_bf16 v[114:129], v[136:139], v[220:223], v[114:129]
	v_fma_f32 v140, v140, s82, v230
	v_exp_f32_e32 v140, v140
	v_fma_f32 v141, v141, s82, v230
	v_exp_f32_e32 v141, v141
	ds_read_b64_tr_b16 v[216:217], v212 offset:50176
	ds_read_b64_tr_b16 v[218:219], v212 offset:54272
	ds_read_b64_tr_b16 v[220:221], v212 offset:58368
	ds_read_b64_tr_b16 v[222:223], v212 offset:62464
	s_waitcnt lgkmcnt(4)
	v_mfma_f32_32x32x16_bf16 v[98:113], v[132:135], v[236:239], v[98:113]
	v_fma_f32 v142, v142, s82, v230
	v_exp_f32_e32 v142, v142
	v_add_f32_e32 v226, v140, v141
	v_fma_f32 v143, v143, s82, v230
	v_exp_f32_e32 v143, v143
	v_mfma_f32_32x32x16_bf16 v[98:113], v[136:139], v[240:243], v[98:113]
	v_add_f32_e32 v226, v226, v142
	v_fma_f32 v144, v144, s82, v230
	v_exp_f32_e32 v144, v144
	v_add_f32_e32 v226, v226, v143
	v_fma_f32 v145, v145, s82, v230
	ds_read_b64_tr_b16 v[236:237], v212 offset:50688
	ds_read_b64_tr_b16 v[238:239], v212 offset:54784
	ds_read_b64_tr_b16 v[240:241], v212 offset:58880
	ds_read_b64_tr_b16 v[242:243], v212 offset:62976
	s_waitcnt lgkmcnt(4)
	v_mfma_f32_32x32x16_bf16 v[82:97], v[132:135], v[216:219], v[82:97]
	v_exp_f32_e32 v145, v145
	v_add_f32_e32 v226, v226, v144
	v_fma_f32 v146, v146, s82, v230
	v_exp_f32_e32 v146, v146
	v_mfma_f32_32x32x16_bf16 v[82:97], v[136:139], v[220:223], v[82:97]
	v_add_f32_e32 v226, v226, v145
	v_fma_f32 v147, v147, s82, v230
	v_exp_f32_e32 v147, v147
	v_add_f32_e32 v226, v226, v146
	v_fma_f32 v148, v148, s82, v230
	ds_read_b64_tr_b16 v[216:217], v212 offset:51200
	ds_read_b64_tr_b16 v[218:219], v212 offset:55296
	ds_read_b64_tr_b16 v[220:221], v212 offset:59392
	ds_read_b64_tr_b16 v[222:223], v212 offset:63488
	s_waitcnt lgkmcnt(4)
	v_mfma_f32_32x32x16_bf16 v[66:81], v[132:135], v[236:239], v[66:81]
	v_exp_f32_e32 v148, v148
	v_add_f32_e32 v226, v226, v147
	v_fma_f32 v149, v149, s82, v230
	v_exp_f32_e32 v149, v149
	v_mfma_f32_32x32x16_bf16 v[66:81], v[136:139], v[240:243], v[66:81]
	v_add_f32_e32 v226, v226, v148
	v_fma_f32 v150, v150, s82, v230
	v_exp_f32_e32 v150, v150
	v_add_f32_e32 v226, v226, v149
	ds_read_b64_tr_b16 v[236:237], v212 offset:51712
	ds_read_b64_tr_b16 v[238:239], v212 offset:55808
	ds_read_b64_tr_b16 v[240:241], v212 offset:59904
	ds_read_b64_tr_b16 v[242:243], v212 offset:64000
	s_waitcnt lgkmcnt(4)
	v_mfma_f32_32x32x16_bf16 v[50:65], v[132:135], v[216:219], v[50:65]
	v_fma_f32 v151, v151, s82, v230
	v_exp_f32_e32 v151, v151
	v_add_f32_e32 v226, v226, v150
	v_fma_f32 v152, v152, s82, v230
	v_mfma_f32_32x32x16_bf16 v[50:65], v[136:139], v[220:223], v[50:65]
	v_exp_f32_e32 v152, v152
	v_add_f32_e32 v226, v226, v151
	v_fma_f32 v153, v153, s82, v230
	v_exp_f32_e32 v153, v153
	ds_read_b64_tr_b16 v[216:217], v212 offset:52224
	ds_read_b64_tr_b16 v[218:219], v212 offset:56320
	ds_read_b64_tr_b16 v[220:221], v212 offset:60416
	ds_read_b64_tr_b16 v[222:223], v212 offset:64512
	s_waitcnt lgkmcnt(4)
	v_mfma_f32_32x32x16_bf16 v[34:49], v[132:135], v[236:239], v[34:49]
	v_add_f32_e32 v226, v226, v152
	v_fma_f32 v154, v154, s82, v230
	v_exp_f32_e32 v154, v154
	v_add_f32_e32 v226, v226, v153
	v_mfma_f32_32x32x16_bf16 v[34:49], v[136:139], v[240:243], v[34:49]
	v_fma_f32 v155, v155, s82, v230
	v_exp_f32_e32 v155, v155
	v_add_f32_e32 v226, v226, v154
	v_exp_f32_e32 v227, v227
	ds_read_b64_tr_b16 v[236:237], v212 offset:52736
	ds_read_b64_tr_b16 v[238:239], v212 offset:56832
	ds_read_b64_tr_b16 v[240:241], v212 offset:60928
	ds_read_b64_tr_b16 v[242:243], v212 offset:65024
	s_waitcnt lgkmcnt(4)
	v_mfma_f32_32x32x16_bf16 v[18:33], v[132:135], v[216:219], v[18:33]
	v_add_f32_e32 v228, v226, v155
	v_cndmask_b32_e64 v227, v227, 1.0, vcc
	v_mov_b32_e32 v229, v228
	v_cvt_pk_bf16_f32 v156, v140, v141
	v_cvt_pk_bf16_f32 v157, v142, v143
	v_mfma_f32_32x32x16_bf16 v[18:33], v[136:139], v[220:223], v[18:33]
	v_cvt_pk_bf16_f32 v158, v144, v145
	v_cvt_pk_bf16_f32 v159, v146, v147
	v_cvt_pk_bf16_f32 v160, v148, v149
	v_cvt_pk_bf16_f32 v161, v150, v151
	v_cvt_pk_bf16_f32 v162, v152, v153
	s_waitcnt lgkmcnt(0)
	v_mfma_f32_32x32x16_bf16 v[2:17], v[132:135], v[236:239], v[2:17]
	v_cvt_pk_bf16_f32 v163, v154, v155
	v_permlane32_swap_b32_e32 v228, v229
	v_permlane32_swap_b32_e32 v156, v158
	v_permlane32_swap_b32_e32 v157, v159
	v_mfma_f32_32x32x16_bf16 v[2:17], v[136:139], v[240:243], v[2:17]
	v_permlane32_swap_b32_e32 v160, v162
	v_permlane32_swap_b32_e32 v161, v163
	v_add_f32_e32 v228, v228, v229
	v_fma_f32 v130, v130, v227, v228
	s_cbranch_vccz .Lattn_rescale0

; #define MFMA32(a, b, c) __builtin_amdgcn_mfma_f32_32x32x16_bf16((a), (b), (c), 0, 0, 0)
; DI void phase_attn(int wid0, const Params& p, int L, unsigned char* lds, bool dry) {
;     ...
;             asm volatile("s_waitcnt vmcnt(0) lgkmcnt(0)" ::: "memory"); __builtin_amdgcn_s_barrier(); asm volatile("" ::: "memory");
;             if (t + 1 < ntiles) attn_stage(kh_ + (size_t)(b * 4096 + 32 * t) * 2048, vh_ + (size_t)(b * 4096 + 32 * t) * 2048, koff, voff, ldsl + 65536 + ((t + 1) & 1) * 32768, wid);
;             const int kpos0 = (t == 0) ? 0 : 16 + 32 * (t - 1);
;             if (kpos0 <= wq0 + 31) {
;                 const unsigned char* Ks = lds + 65536 + (t & 1) * 32768 + psub * 8192;
;                 f32x16 p0, p0b;
; #pragma unroll
;                 for (int r = 0; r < 16; ++r) { p0[r] = 0.f; p0b[r] = 0.f; }
;                 int swz = (r32 & 6) << 4, kro = r32 * 256 + ((hi ^ (r32 & 1)) << 4); asm volatile("" : "+v"(swz), "+v"(kro));
; #pragma unroll
;                 for (int d0 = 0; d0 < 8; d0 += 2) {
;                     const bf16x8 b0 = *(const bf16x8*)(Ks + kro + ((d0 * 32) ^ swz));
;                     const bf16x8 qf = *(const bf16x8*)(qlds + d0 * 1024);
;                     const bf16x8 b1 = *(const bf16x8*)(Ks + kro + (((d0 + 1) * 32) ^ swz));
;                     const bf16x8 qg = *(const bf16x8*)(qlds + (d0 + 1) * 1024);
;                     p0 = MFMA32(b0, qf, p0);
;                     p0b = MFMA32(b1, qg, p0b);
;                     if (d0 == 2) __builtin_amdgcn_sched_barrier(0);
;                 }
; #pragma unroll
;                 for (int r = 0; r < 16; ++r) p0[r] += p0b[r];
;                 __builtin_amdgcn_sched_barrier(0);
;                 if (t > 0 && wq0 - (kpos0 + 31) >= 128) {
.Lattn_top1:
	s_waitcnt vmcnt(0) lgkmcnt(0)
	s_barrier
	s_max_i32 s48, s7, 0
	s_cmp_gt_i32 s48, s38
	s_cbranch_scc1 .Lattn_skip1
	ds_read_b128 v[216:219], v188 offset:32768
	ds_read_b128 v[220:223], v177 offset:32768
	ds_read_b128 v[236:239], v209 offset:32768
	ds_read_b128 v[240:243], v210 offset:32768
	s_waitcnt lgkmcnt(2)
	v_mfma_f32_32x32x16_bf16 v[140:155], v[216:219], v[248:251], 0
	s_add_i32 m0, s4, 0x0
	v_mfma_f32_32x32x16_bf16 v[140:155], v[220:223], v[252:255], v[140:155]
	global_load_lds_dwordx4 v131, s[88:89]
	ds_read_b128 v[216:219], v211 offset:32768
	ds_read_b128 v[220:223], v215 offset:32768
	s_waitcnt lgkmcnt(2)
	v_mfma_f32_32x32x16_bf16 v[140:155], v[236:239], v[200:203], v[140:155]
	s_add_i32 m0, s4, 0x2000
	v_mfma_f32_32x32x16_bf16 v[140:155], v[240:243], v[204:207], v[140:155]
	global_load_lds_dwordx4 v131, s[90:91]
	v_add_u32_e32 v131, 0x20000, v131
	ds_read_b128 v[236:239], v224 offset:32768
	ds_read_b128 v[240:243], v225 offset:32768
	s_waitcnt lgkmcnt(2)
	v_mfma_f32_32x32x16_bf16 v[140:155], v[216:219], v[164:167], v[140:155]
	s_add_i32 m0, s96, 0x8000
	v_mfma_f32_32x32x16_bf16 v[140:155], v[220:223], v[168:171], v[140:155]
	global_load_lds_dwordx4 v208, s[92:93]
	s_waitcnt lgkmcnt(0)
	v_mfma_f32_32x32x16_bf16 v[140:155], v[236:239], v[172:175], v[140:155]
	s_add_i32 m0, s96, 0xa000
	v_mfma_f32_32x32x16_bf16 v[140:155], v[240:243], v[232:235], v[140:155]
	global_load_lds_dwordx4 v208, s[94:95]
	v_add_u32_e32 v208, 0x20000, v208
	s_cmpk_gt_i32 s39, 0x7f
	s_cbranch_scc0 .Lattn_near1
	s_cmp_lg_u32 s67, 1
	s_cbranch_scc0 .Lattn_near1

; DI void phase_attn(int wid0, const Params& p, int L, unsigned char* lds, bool dry) {
;     ...
;                 float pmax = p0[0];
; #pragma unroll
;                 for (int r = 1; r < 16; ++r) pmax = fmaxf(pmax, p0[r]);
;                 { auto rr = __builtin_amdgcn_permlane32_swap(__float_as_uint(pmax), __float_as_uint(pmax), false, false); pmax = fmaxf(__uint_as_float(rr[0]), __uint_as_float(rr[1])); }
;                 float mn, alpha;
;                 if (__all(pmax - m_reg <= ATT_THR2)) { mn = m_reg; alpha = 1.f; }
;                 else { mn = fmaxf(m_reg, pmax); alpha = __builtin_amdgcn_exp2f(m_reg - mn); m_reg = mn; }
;                 float ps = 0.f;
; #pragma unroll
;                 for (int r = 0; r < 16; ++r) { p0[r] = __builtin_amdgcn_exp2f(p0[r] - mn); ps += p0[r]; }
;                 { auto rr = __builtin_amdgcn_permlane32_swap(__float_as_uint(ps), __float_as_uint(ps), false, false); ps = __uint_as_float(rr[0]) + __uint_as_float(rr[1]); }
;                 l_reg = l_reg * alpha + ps;
;                 __builtin_amdgcn_sched_barrier(0);
;                 bf16x8 pa0, pa1;
;     ...
;                 PK4(p0, 0, pa0); PK4(p0, 8, pa1);
;     ...
;                 __builtin_amdgcn_sched_barrier(0);
;                 if (__any(alpha < 1.f)) {
;                     if (hi == 0) al_l[r32] = alpha;
;                     asm volatile("s_waitcnt lgkmcnt(0)" ::: "memory");
;                     float ar[16];
; #pragma unroll
;                     for (int r = 0; r < 16; ++r) ar[r] = al_l[crow(r, hi)];
; #pragma unroll
;                     for (int d = 0; d < 8; ++d)
; #pragma unroll
;                         for (int r = 0; r < 16; ++r) o[d][r] *= ar[r];
;                 }
;                 __builtin_amdgcn_sched_barrier(0);
;                 LAS unsigned char* vbp = ldsl + 65536 + (t & 1) * 32768 + 16384 + v_rd_base(lane);
;                 __builtin_amdgcn_s_setprio(1);
;     ...
;                 {
;                     s16x4 a0, a1, a2, a3, b0_, b1_, b2_, b3_;
;                     PV_RD(0, a0, a1, a2, a3); SB();
;                     PV_RD(1, b0_, b1_, b2_, b3_); SB(); PV_MM(0, a0, a1, a2, a3); SB();
;                     PV_RD(2, a0, a1, a2, a3); SB(); PV_MM(1, b0_, b1_, b2_, b3_); SB();
;                     PV_RD(3, b0_, b1_, b2_, b3_); SB(); PV_MM(2, a0, a1, a2, a3); SB();
;                     PV_RD(4, a0, a1, a2, a3); SB(); PV_MM(3, b0_, b1_, b2_, b3_); SB();
.Lattn_region1:
	ds_read_b64_tr_b16 v[216:217], v212 offset:0
	ds_read_b64_tr_b16 v[218:219], v212 offset:4096
	ds_read_b64_tr_b16 v[220:221], v212 offset:8192
	ds_read_b64_tr_b16 v[222:223], v212 offset:12288
	ds_read_b64_tr_b16 v[236:237], v212 offset:512
	ds_read_b64_tr_b16 v[238:239], v212 offset:4608
	ds_read_b64_tr_b16 v[240:241], v212 offset:8704
	ds_read_b64_tr_b16 v[242:243], v212 offset:12800
	v_max3_f32 v226, v140, v141, v142
	v_max3_f32 v226, v226, v143, v144
	v_max3_f32 v226, v226, v145, v146
	v_max3_f32 v226, v226, v147, v148
	v_max3_f32 v226, v226, v149, v150
	v_max3_f32 v226, v226, v151, v152
	v_max3_f32 v226, v226, v153, v154
	v_max_f32_e32 v226, v226, v155
	v_mov_b32_e32 v227, v226
	s_nop 1
	v_permlane32_swap_b32_e32 v226, v227
	v_max_f32_e32 v226, v226, v227
	v_fma_f32 v226, v226, s82, v231
	v_sub_f32_e32 v227, v226, v213
	v_cmp_ge_f32_e32 vcc, s97, v227
	s_cmp_eq_u64 vcc, exec
	v_max_f32_e32 v226, v213, v226
	s_cselect_b64 vcc, -1, 0
	v_sub_f32_e32 v227, v213, v226
	v_cndmask_b32_e32 v213, v226, v213, vcc
	v_sub_f32_e32 v230, v231, v213
	s_waitcnt lgkmcnt(4)
	v_mfma_f32_32x32x16_bf16 v[114:129], v[156:159], v[216:219], v[114:129]
	v_mfma_f32_32x32x16_bf16 v[114:129], v[160:163], v[220:223], v[114:129]
	v_fma_f32 v140, v140, s82, v230
	v_exp_f32_e32 v140, v140
	v_fma_f32 v141, v141, s82, v230
	v_exp_f32_e32 v141, v141
	ds_read_b64_tr_b16 v[216:217], v212 offset:1024
	ds_read_b64_tr_b16 v[218:219], v212 offset:5120
	ds_read_b64_tr_b16 v[220:221], v212 offset:9216
	ds_read_b64_tr_b16 v[222:223], v212 offset:13312
	s_waitcnt lgkmcnt(4)
	v_mfma_f32_32x32x16_bf16 v[98:113], v[156:159], v[236:239], v[98:113]
	v_fma_f32 v142, v142, s82, v230
	v_exp_f32_e32 v142, v142
	v_add_f32_e32 v226, v140, v141
	v_fma_f32 v143, v143, s82, v230
	v_exp_f32_e32 v143, v143
	v_mfma_f32_32x32x16_bf16 v[98:113], v[160:163], v[240:243], v[98:113]
	v_add_f32_e32 v226, v226, v142
	v_fma_f32 v144, v144, s82, v230
	v_exp_f32_e32 v144, v144
	v_add_f32_e32 v226, v226, v143
	v_fma_f32 v145, v145, s82, v230
	ds_read_b64_tr_b16 v[236:237], v212 offset:1536
	ds_read_b64_tr_b16 v[238:239], v212 offset:5632
	ds_read_b64_tr_b16 v[240:241], v212 offset:9728
	ds_read_b64_tr_b16 v[242:243], v212 offset:13824
	s_waitcnt lgkmcnt(4)
	v_mfma_f32_32x32x16_bf16 v[82:97], v[156:159], v[216:219], v[82:97]
	v_exp_f32_e32 v145, v145
	v_add_f32_e32 v226, v226, v144
	v_fma_f32 v146, v146, s82, v230
	v_exp_f32_e32 v146, v146
	v_mfma_f32_32x32x16_bf16 v[82:97], v[160:163], v[220:223], v[82:97]
	v_add_f32_e32 v226, v226, v145
	v_fma_f32 v147, v147, s82, v230
	v_exp_f32_e32 v147, v147
	v_add_f32_e32 v226, v226, v146
	v_fma_f32 v148, v148, s82, v230
	ds_read_b64_tr_b16 v[216:217], v212 offset:2048
	ds_read_b64_tr_b16 v[218:219], v212 offset:6144
	ds_read_b64_tr_b16 v[220:221], v212 offset:10240
	ds_read_b64_tr_b16 v[222:223], v212 offset:14336
	s_waitcnt lgkmcnt(4)
	v_mfma_f32_32x32x16_bf16 v[66:81], v[156:159], v[236:239], v[66:81]
	v_exp_f32_e32 v148, v148
	v_add_f32_e32 v226, v226, v147
	v_fma_f32 v149, v149, s82, v230
	v_exp_f32_e32 v149, v149
	v_mfma_f32_32x32x16_bf16 v[66:81], v[160:163], v[240:243], v[66:81]
	v_add_f32_e32 v226, v226, v148
	v_fma_f32 v150, v150, s82, v230
	v_exp_f32_e32 v150, v150
	v_add_f32_e32 v226, v226, v149
	ds_read_b64_tr_b16 v[236:237], v212 offset:2560
	ds_read_b64_tr_b16 v[238:239], v212 offset:6656
	ds_read_b64_tr_b16 v[240:241], v212 offset:10752
	ds_read_b64_tr_b16 v[242:243], v212 offset:14848
	s_waitcnt lgkmcnt(4)
	v_mfma_f32_32x32x16_bf16 v[50:65], v[156:159], v[216:219], v[50:65]
	v_fma_f32 v151, v151, s82, v230
	v_exp_f32_e32 v151, v151
	v_add_f32_e32 v226, v226, v150
	v_fma_f32 v152, v152, s82, v230
	v_mfma_f32_32x32x16_bf16 v[50:65], v[160:163], v[220:223], v[50:65]
	v_exp_f32_e32 v152, v152
	v_add_f32_e32 v226, v226, v151
	v_fma_f32 v153, v153, s82, v230
	v_exp_f32_e32 v153, v153
	ds_read_b64_tr_b16 v[216:217], v212 offset:3072
	ds_read_b64_tr_b16 v[218:219], v212 offset:7168
	ds_read_b64_tr_b16 v[220:221], v212 offset:11264
	ds_read_b64_tr_b16 v[222:223], v212 offset:15360
	s_waitcnt lgkmcnt(4)
	v_mfma_f32_32x32x16_bf16 v[34:49], v[156:159], v[236:239], v[34:49]
	v_add_f32_e32 v226, v226, v152
	v_fma_f32 v154, v154, s82, v230
	v_exp_f32_e32 v154, v154
	v_add_f32_e32 v226, v226, v153
	v_mfma_f32_32x32x16_bf16 v[34:49], v[160:163], v[240:243], v[34:49]
	v_fma_f32 v155, v155, s82, v230
	v_exp_f32_e32 v155, v155
	v_add_f32_e32 v226, v226, v154
	v_exp_f32_e32 v227, v227
	ds_read_b64_tr_b16 v[236:237], v212 offset:3584
	ds_read_b64_tr_b16 v[238:239], v212 offset:7680
	ds_read_b64_tr_b16 v[240:241], v212 offset:11776
	ds_read_b64_tr_b16 v[242:243], v212 offset:15872
	s_waitcnt lgkmcnt(4)
	v_mfma_f32_32x32x16_bf16 v[18:33], v[156:159], v[216:219], v[18:33]
	v_add_f32_e32 v228, v226, v155
	v_cndmask_b32_e64 v227, v227, 1.0, vcc
	v_mov_b32_e32 v229, v228
	v_cvt_pk_bf16_f32 v132, v140, v141
	v_cvt_pk_bf16_f32 v133, v142, v143
	v_mfma_f32_32x32x16_bf16 v[18:33], v[160:163], v[220:223], v[18:33]
	v_cvt_pk_bf16_f32 v134, v144, v145
	v_cvt_pk_bf16_f32 v135, v146, v147
	v_cvt_pk_bf16_f32 v136, v148, v149
	v_cvt_pk_bf16_f32 v137, v150, v151
	v_cvt_pk_bf16_f32 v138, v152, v153
	s_waitcnt lgkmcnt(0)
	v_mfma_f32_32x32x16_bf16 v[2:17], v[156:159], v[236:239], v[2:17]
	v_cvt_pk_bf16_f32 v139, v154, v155
	v_permlane32_swap_b32_e32 v228, v229
	v_permlane32_swap_b32_e32 v132, v134
	v_permlane32_swap_b32_e32 v133, v135
	v_mfma_f32_32x32x16_bf16 v[2:17], v[160:163], v[240:243], v[2:17]
	v_permlane32_swap_b32_e32 v136, v138
	v_permlane32_swap_b32_e32 v137, v139
	v_add_f32_e32 v228, v228, v229
	v_fma_f32 v130, v130, v227, v228
	s_cbranch_vccz .Lattn_rescale1

; #define MFMA32(a, b, c) __builtin_amdgcn_mfma_f32_32x32x16_bf16((a), (b), (c), 0, 0, 0)
; DI void phase_attn(int wid0, const Params& p, int L, unsigned char* lds, bool dry) {
;     ...
;             asm volatile("s_waitcnt vmcnt(0) lgkmcnt(0)" ::: "memory"); __builtin_amdgcn_s_barrier(); asm volatile("" ::: "memory");
;             if (t + 1 < ntiles) attn_stage(kh_ + (size_t)(b * 4096 + 32 * t) * 2048, vh_ + (size_t)(b * 4096 + 32 * t) * 2048, koff, voff, ldsl + 65536 + ((t + 1) & 1) * 32768, wid);
;             const int kpos0 = (t == 0) ? 0 : 16 + 32 * (t - 1);
;             if (kpos0 <= wq0 + 31) {
;                 const unsigned char* Ks = lds + 65536 + (t & 1) * 32768 + psub * 8192;
;                 f32x16 p0, p0b;
; #pragma unroll
;                 for (int r = 0; r < 16; ++r) { p0[r] = 0.f; p0b[r] = 0.f; }
;                 int swz = (r32 & 6) << 4, kro = r32 * 256 + ((hi ^ (r32 & 1)) << 4); asm volatile("" : "+v"(swz), "+v"(kro));
; #pragma unroll
;                 for (int d0 = 0; d0 < 8; d0 += 2) {
;                     const bf16x8 b0 = *(const bf16x8*)(Ks + kro + ((d0 * 32) ^ swz));
;                     const bf16x8 qf = *(const bf16x8*)(qlds + d0 * 1024);
;                     const bf16x8 b1 = *(const bf16x8*)(Ks + kro + (((d0 + 1) * 32) ^ swz));
;                     const bf16x8 qg = *(const bf16x8*)(qlds + (d0 + 1) * 1024);
;                     p0 = MFMA32(b0, qf, p0);
;                     p0b = MFMA32(b1, qg, p0b);
;                     if (d0 == 2) __builtin_amdgcn_sched_barrier(0);
;                 }
; #pragma unroll
;                 for (int r = 0; r < 16; ++r) p0[r] += p0b[r];
;                 __builtin_amdgcn_sched_barrier(0);
;                 if (t > 0 && wq0 - (kpos0 + 31) >= 128) {
.Lattn_top2:
	s_waitcnt vmcnt(0) lgkmcnt(0)
	s_barrier
	s_max_i32 s48, s7, 0
	s_cmp_gt_i32 s48, s38
	s_cbranch_scc1 .Lattn_skip2
	ds_read_b128 v[216:219], v188
	ds_read_b128 v[220:223], v177
	ds_read_b128 v[236:239], v209
	ds_read_b128 v[240:243], v210
	s_waitcnt lgkmcnt(2)
	v_mfma_f32_32x32x16_bf16 v[140:155], v[216:219], v[248:251], 0
	s_add_i32 m0, s4, 0x8000
	v_mfma_f32_32x32x16_bf16 v[140:155], v[220:223], v[252:255], v[140:155]
	global_load_lds_dwordx4 v131, s[88:89]
	ds_read_b128 v[216:219], v211
	ds_read_b128 v[220:223], v215
	s_waitcnt lgkmcnt(2)
	v_mfma_f32_32x32x16_bf16 v[140:155], v[236:239], v[200:203], v[140:155]
	s_add_i32 m0, s4, 0xa000
	v_mfma_f32_32x32x16_bf16 v[140:155], v[240:243], v[204:207], v[140:155]
	global_load_lds_dwordx4 v131, s[90:91]
	v_add_u32_e32 v131, 0x20000, v131
	ds_read_b128 v[236:239], v224
	ds_read_b128 v[240:243], v225
	s_waitcnt lgkmcnt(2)
	v_mfma_f32_32x32x16_bf16 v[140:155], v[216:219], v[164:167], v[140:155]
	s_add_i32 m0, s96, 0xc000
	v_mfma_f32_32x32x16_bf16 v[140:155], v[220:223], v[168:171], v[140:155]
	global_load_lds_dwordx4 v208, s[92:93]
	s_waitcnt lgkmcnt(0)
	v_mfma_f32_32x32x16_bf16 v[140:155], v[236:239], v[172:175], v[140:155]
	s_add_i32 m0, s96, 0xe000
	v_mfma_f32_32x32x16_bf16 v[140:155], v[240:243], v[232:235], v[140:155]
	global_load_lds_dwordx4 v208, s[94:95]
	v_add_u32_e32 v208, 0x20000, v208
	s_cmpk_gt_i32 s39, 0x7f
	s_cbranch_scc0 .Lattn_near2
	s_cmp_lg_u32 s67, 1
	s_cbranch_scc0 .Lattn_near2

; DI void phase_attn(int wid0, const Params& p, int L, unsigned char* lds, bool dry) {
;     ...
;                 float pmax = p0[0];
; #pragma unroll
;                 for (int r = 1; r < 16; ++r) pmax = fmaxf(pmax, p0[r]);
;                 { auto rr = __builtin_amdgcn_permlane32_swap(__float_as_uint(pmax), __float_as_uint(pmax), false, false); pmax = fmaxf(__uint_as_float(rr[0]), __uint_as_float(rr[1])); }
;                 float mn, alpha;
;                 if (__all(pmax - m_reg <= ATT_THR2)) { mn = m_reg; alpha = 1.f; }
;                 else { mn = fmaxf(m_reg, pmax); alpha = __builtin_amdgcn_exp2f(m_reg - mn); m_reg = mn; }
;                 float ps = 0.f;
; #pragma unroll
;                 for (int r = 0; r < 16; ++r) { p0[r] = __builtin_amdgcn_exp2f(p0[r] - mn); ps += p0[r]; }
;                 { auto rr = __builtin_amdgcn_permlane32_swap(__float_as_uint(ps), __float_as_uint(ps), false, false); ps = __uint_as_float(rr[0]) + __uint_as_float(rr[1]); }
;                 l_reg = l_reg * alpha + ps;
;                 __builtin_amdgcn_sched_barrier(0);
;                 bf16x8 pa0, pa1;
;     ...
;                 PK4(p0, 0, pa0); PK4(p0, 8, pa1);
;     ...
;                 __builtin_amdgcn_sched_barrier(0);
;                 if (__any(alpha < 1.f)) {
;                     if (hi == 0) al_l[r32] = alpha;
;                     asm volatile("s_waitcnt lgkmcnt(0)" ::: "memory");
;                     float ar[16];
; #pragma unroll
;                     for (int r = 0; r < 16; ++r) ar[r] = al_l[crow(r, hi)];
; #pragma unroll
;                     for (int d = 0; d < 8; ++d)
; #pragma unroll
;                         for (int r = 0; r < 16; ++r) o[d][r] *= ar[r];
;                 }
;                 __builtin_amdgcn_sched_barrier(0);
;                 LAS unsigned char* vbp = ldsl + 65536 + (t & 1) * 32768 + 16384 + v_rd_base(lane);
;                 __builtin_amdgcn_s_setprio(1);
;     ...
;                 {
;                     s16x4 a0, a1, a2, a3, b0_, b1_, b2_, b3_;
;                     PV_RD(0, a0, a1, a2, a3); SB();
;                     PV_RD(1, b0_, b1_, b2_, b3_); SB(); PV_MM(0, a0, a1, a2, a3); SB();
;                     PV_RD(2, a0, a1, a2, a3); SB(); PV_MM(1, b0_, b1_, b2_, b3_); SB();
;                     PV_RD(3, b0_, b1_, b2_, b3_); SB(); PV_MM(2, a0, a1, a2, a3); SB();
;                     PV_RD(4, a0, a1, a2, a3); SB(); PV_MM(3, b0_, b1_, b2_, b3_); SB();
.Lattn_region2:
	ds_read_b64_tr_b16 v[216:217], v212 offset:16384
	ds_read_b64_tr_b16 v[218:219], v212 offset:20480
	ds_read_b64_tr_b16 v[220:221], v212 offset:24576
	ds_read_b64_tr_b16 v[222:223], v212 offset:28672
	ds_read_b64_tr_b16 v[236:237], v212 offset:16896
	ds_read_b64_tr_b16 v[238:239], v212 offset:20992
	ds_read_b64_tr_b16 v[240:241], v212 offset:25088
	ds_read_b64_tr_b16 v[242:243], v212 offset:29184
	v_max3_f32 v226, v140, v141, v142
	v_max3_f32 v226, v226, v143, v144
	v_max3_f32 v226, v226, v145, v146
	v_max3_f32 v226, v226, v147, v148
	v_max3_f32 v226, v226, v149, v150
	v_max3_f32 v226, v226, v151, v152
	v_max3_f32 v226, v226, v153, v154
	v_max_f32_e32 v226, v226, v155
	v_mov_b32_e32 v227, v226
	s_nop 1
	v_permlane32_swap_b32_e32 v226, v227
	v_max_f32_e32 v226, v226, v227
	v_fma_f32 v226, v226, s82, v231
	v_sub_f32_e32 v227, v226, v213
	v_cmp_ge_f32_e32 vcc, s97, v227
	s_cmp_eq_u64 vcc, exec
	v_max_f32_e32 v226, v213, v226
	s_cselect_b64 vcc, -1, 0
	v_sub_f32_e32 v227, v213, v226
	v_cndmask_b32_e32 v213, v226, v213, vcc
	v_sub_f32_e32 v230, v231, v213
	s_waitcnt lgkmcnt(4)
	v_mfma_f32_32x32x16_bf16 v[114:129], v[132:135], v[216:219], v[114:129]
	v_mfma_f32_32x32x16_bf16 v[114:129], v[136:139], v[220:223], v[114:129]
	v_fma_f32 v140, v140, s82, v230
	v_exp_f32_e32 v140, v140
	v_fma_f32 v141, v141, s82, v230
	v_exp_f32_e32 v141, v141
	ds_read_b64_tr_b16 v[216:217], v212 offset:17408
	ds_read_b64_tr_b16 v[218:219], v212 offset:21504
	ds_read_b64_tr_b16 v[220:221], v212 offset:25600
	ds_read_b64_tr_b16 v[222:223], v212 offset:29696
	s_waitcnt lgkmcnt(4)
	v_mfma_f32_32x32x16_bf16 v[98:113], v[132:135], v[236:239], v[98:113]
	v_fma_f32 v142, v142, s82, v230
	v_exp_f32_e32 v142, v142
	v_add_f32_e32 v226, v140, v141
	v_fma_f32 v143, v143, s82, v230
	v_exp_f32_e32 v143, v143
	v_mfma_f32_32x32x16_bf16 v[98:113], v[136:139], v[240:243], v[98:113]
	v_add_f32_e32 v226, v226, v142
	v_fma_f32 v144, v144, s82, v230
	v_exp_f32_e32 v144, v144
	v_add_f32_e32 v226, v226, v143
	v_fma_f32 v145, v145, s82, v230
	ds_read_b64_tr_b16 v[236:237], v212 offset:17920
	ds_read_b64_tr_b16 v[238:239], v212 offset:22016
	ds_read_b64_tr_b16 v[240:241], v212 offset:26112
	ds_read_b64_tr_b16 v[242:243], v212 offset:30208
	s_waitcnt lgkmcnt(4)
	v_mfma_f32_32x32x16_bf16 v[82:97], v[132:135], v[216:219], v[82:97]
	v_exp_f32_e32 v145, v145
	v_add_f32_e32 v226, v226, v144
	v_fma_f32 v146, v146, s82, v230
	v_exp_f32_e32 v146, v146
	v_mfma_f32_32x32x16_bf16 v[82:97], v[136:139], v[220:223], v[82:97]
	v_add_f32_e32 v226, v226, v145
	v_fma_f32 v147, v147, s82, v230
	v_exp_f32_e32 v147, v147
	v_add_f32_e32 v226, v226, v146
	v_fma_f32 v148, v148, s82, v230
	ds_read_b64_tr_b16 v[216:217], v212 offset:18432
	ds_read_b64_tr_b16 v[218:219], v212 offset:22528
	ds_read_b64_tr_b16 v[220:221], v212 offset:26624
	ds_read_b64_tr_b16 v[222:223], v212 offset:30720
	s_waitcnt lgkmcnt(4)
	v_mfma_f32_32x32x16_bf16 v[66:81], v[132:135], v[236:239], v[66:81]
	v_exp_f32_e32 v148, v148
	v_add_f32_e32 v226, v226, v147
	v_fma_f32 v149, v149, s82, v230
	v_exp_f32_e32 v149, v149
	v_mfma_f32_32x32x16_bf16 v[66:81], v[136:139], v[240:243], v[66:81]
	v_add_f32_e32 v226, v226, v148
	v_fma_f32 v150, v150, s82, v230
	v_exp_f32_e32 v150, v150
	v_add_f32_e32 v226, v226, v149
	ds_read_b64_tr_b16 v[236:237], v212 offset:18944
	ds_read_b64_tr_b16 v[238:239], v212 offset:23040
	ds_read_b64_tr_b16 v[240:241], v212 offset:27136
	ds_read_b64_tr_b16 v[242:243], v212 offset:31232
	s_waitcnt lgkmcnt(4)
	v_mfma_f32_32x32x16_bf16 v[50:65], v[132:135], v[216:219], v[50:65]
	v_fma_f32 v151, v151, s82, v230
	v_exp_f32_e32 v151, v151
	v_add_f32_e32 v226, v226, v150
	v_fma_f32 v152, v152, s82, v230
	v_mfma_f32_32x32x16_bf16 v[50:65], v[136:139], v[220:223], v[50:65]
	v_exp_f32_e32 v152, v152
	v_add_f32_e32 v226, v226, v151
	v_fma_f32 v153, v153, s82, v230
	v_exp_f32_e32 v153, v153
	ds_read_b64_tr_b16 v[216:217], v212 offset:19456
	ds_read_b64_tr_b16 v[218:219], v212 offset:23552
	ds_read_b64_tr_b16 v[220:221], v212 offset:27648
	ds_read_b64_tr_b16 v[222:223], v212 offset:31744
	s_waitcnt lgkmcnt(4)
	v_mfma_f32_32x32x16_bf16 v[34:49], v[132:135], v[236:239], v[34:49]
	v_add_f32_e32 v226, v226, v152
	v_fma_f32 v154, v154, s82, v230
	v_exp_f32_e32 v154, v154
	v_add_f32_e32 v226, v226, v153
	v_mfma_f32_32x32x16_bf16 v[34:49], v[136:139], v[240:243], v[34:49]
	v_fma_f32 v155, v155, s82, v230
	v_exp_f32_e32 v155, v155
	v_add_f32_e32 v226, v226, v154
	v_exp_f32_e32 v227, v227
	ds_read_b64_tr_b16 v[236:237], v212 offset:19968
	ds_read_b64_tr_b16 v[238:239], v212 offset:24064
	ds_read_b64_tr_b16 v[240:241], v212 offset:28160
	ds_read_b64_tr_b16 v[242:243], v212 offset:32256
	s_waitcnt lgkmcnt(4)
	v_mfma_f32_32x32x16_bf16 v[18:33], v[132:135], v[216:219], v[18:33]
	v_add_f32_e32 v228, v226, v155
	v_cndmask_b32_e64 v227, v227, 1.0, vcc
	v_mov_b32_e32 v229, v228
	v_cvt_pk_bf16_f32 v156, v140, v141
	v_cvt_pk_bf16_f32 v157, v142, v143
	v_mfma_f32_32x32x16_bf16 v[18:33], v[136:139], v[220:223], v[18:33]
	v_cvt_pk_bf16_f32 v158, v144, v145
	v_cvt_pk_bf16_f32 v159, v146, v147
	v_cvt_pk_bf16_f32 v160, v148, v149
	v_cvt_pk_bf16_f32 v161, v150, v151
	v_cvt_pk_bf16_f32 v162, v152, v153
	s_waitcnt lgkmcnt(0)
	v_mfma_f32_32x32x16_bf16 v[2:17], v[132:135], v[236:239], v[2:17]
	v_cvt_pk_bf16_f32 v163, v154, v155
	v_permlane32_swap_b32_e32 v228, v229
	v_permlane32_swap_b32_e32 v156, v158
	v_permlane32_swap_b32_e32 v157, v159
	v_mfma_f32_32x32x16_bf16 v[2:17], v[136:139], v[240:243], v[2:17]
	v_permlane32_swap_b32_e32 v160, v162
	v_permlane32_swap_b32_e32 v161, v163
	v_add_f32_e32 v228, v228, v229
	v_fma_f32 v130, v130, v227, v228
	s_cbranch_vccz .Lattn_rescale2

; #define MFMA32(a, b, c) __builtin_amdgcn_mfma_f32_32x32x16_bf16((a), (b), (c), 0, 0, 0)
; DI void phase_attn(int wid0, const Params& p, int L, unsigned char* lds, bool dry) {
;     ...
;             asm volatile("s_waitcnt vmcnt(0) lgkmcnt(0)" ::: "memory"); __builtin_amdgcn_s_barrier(); asm volatile("" ::: "memory");
;             if (t + 1 < ntiles) attn_stage(kh_ + (size_t)(b * 4096 + 32 * t) * 2048, vh_ + (size_t)(b * 4096 + 32 * t) * 2048, koff, voff, ldsl + 65536 + ((t + 1) & 1) * 32768, wid);
;             const int kpos0 = (t == 0) ? 0 : 16 + 32 * (t - 1);
;             if (kpos0 <= wq0 + 31) {
;                 const unsigned char* Ks = lds + 65536 + (t & 1) * 32768 + psub * 8192;
;                 f32x16 p0, p0b;
; #pragma unroll
;                 for (int r = 0; r < 16; ++r) { p0[r] = 0.f; p0b[r] = 0.f; }
;                 int swz = (r32 & 6) << 4, kro = r32 * 256 + ((hi ^ (r32 & 1)) << 4); asm volatile("" : "+v"(swz), "+v"(kro));
; #pragma unroll
;                 for (int d0 = 0; d0 < 8; d0 += 2) {
;                     const bf16x8 b0 = *(const bf16x8*)(Ks + kro + ((d0 * 32) ^ swz));
;                     const bf16x8 qf = *(const bf16x8*)(qlds + d0 * 1024);
;                     const bf16x8 b1 = *(const bf16x8*)(Ks + kro + (((d0 + 1) * 32) ^ swz));
;                     const bf16x8 qg = *(const bf16x8*)(qlds + (d0 + 1) * 1024);
;                     p0 = MFMA32(b0, qf, p0);
;                     p0b = MFMA32(b1, qg, p0b);
;                     if (d0 == 2) __builtin_amdgcn_sched_barrier(0);
;                 }
; #pragma unroll
;                 for (int r = 0; r < 16; ++r) p0[r] += p0b[r];
;                 __builtin_amdgcn_sched_barrier(0);
;                 if (t > 0 && wq0 - (kpos0 + 31) >= 128) {
.Lattn_top3:
	s_waitcnt vmcnt(0) lgkmcnt(0)
	s_barrier
	s_max_i32 s48, s7, 0
	s_cmp_gt_i32 s48, s38
	s_cbranch_scc1 .Lattn_skip3
	ds_read_b128 v[216:219], v188 offset:32768
	ds_read_b128 v[220:223], v177 offset:32768
	ds_read_b128 v[236:239], v209 offset:32768
	ds_read_b128 v[240:243], v210 offset:32768
	s_waitcnt lgkmcnt(2)
	v_mfma_f32_32x32x16_bf16 v[140:155], v[216:219], v[248:251], 0
	s_add_i32 m0, s4, 0x0
	v_mfma_f32_32x32x16_bf16 v[140:155], v[220:223], v[252:255], v[140:155]
	global_load_lds_dwordx4 v131, s[88:89]
	ds_read_b128 v[216:219], v211 offset:32768
	ds_read_b128 v[220:223], v215 offset:32768
	s_waitcnt lgkmcnt(2)
	v_mfma_f32_32x32x16_bf16 v[140:155], v[236:239], v[200:203], v[140:155]
	s_add_i32 m0, s4, 0x2000
	v_mfma_f32_32x32x16_bf16 v[140:155], v[240:243], v[204:207], v[140:155]
	global_load_lds_dwordx4 v131, s[90:91]
	v_add_u32_e32 v131, 0x20000, v131
	ds_read_b128 v[236:239], v224 offset:32768
	ds_read_b128 v[240:243], v225 offset:32768
	s_waitcnt lgkmcnt(2)
	v_mfma_f32_32x32x16_bf16 v[140:155], v[216:219], v[164:167], v[140:155]
	s_add_i32 m0, s96, 0x0
	v_mfma_f32_32x32x16_bf16 v[140:155], v[220:223], v[168:171], v[140:155]
	global_load_lds_dwordx4 v208, s[92:93]
	s_waitcnt lgkmcnt(0)
	v_mfma_f32_32x32x16_bf16 v[140:155], v[236:239], v[172:175], v[140:155]
	s_add_i32 m0, s96, 0x2000
	v_mfma_f32_32x32x16_bf16 v[140:155], v[240:243], v[232:235], v[140:155]
	global_load_lds_dwordx4 v208, s[94:95]
	v_add_u32_e32 v208, 0x20000, v208
	s_cmpk_gt_i32 s39, 0x7f
	s_cbranch_scc0 .Lattn_near3
	s_cmp_lg_u32 s67, 1
	s_cbranch_scc0 .Lattn_near3

; DI void phase_attn(int wid0, const Params& p, int L, unsigned char* lds, bool dry) {
;     ...
;                 float pmax = p0[0];
; #pragma unroll
;                 for (int r = 1; r < 16; ++r) pmax = fmaxf(pmax, p0[r]);
;                 { auto rr = __builtin_amdgcn_permlane32_swap(__float_as_uint(pmax), __float_as_uint(pmax), false, false); pmax = fmaxf(__uint_as_float(rr[0]), __uint_as_float(rr[1])); }
;                 float mn, alpha;
;                 if (__all(pmax - m_reg <= ATT_THR2)) { mn = m_reg; alpha = 1.f; }
;                 else { mn = fmaxf(m_reg, pmax); alpha = __builtin_amdgcn_exp2f(m_reg - mn); m_reg = mn; }
;                 float ps = 0.f;
; #pragma unroll
;                 for (int r = 0; r < 16; ++r) { p0[r] = __builtin_amdgcn_exp2f(p0[r] - mn); ps += p0[r]; }
;                 { auto rr = __builtin_amdgcn_permlane32_swap(__float_as_uint(ps), __float_as_uint(ps), false, false); ps = __uint_as_float(rr[0]) + __uint_as_float(rr[1]); }
;                 l_reg = l_reg * alpha + ps;
;                 __builtin_amdgcn_sched_barrier(0);
;                 bf16x8 pa0, pa1;
;     ...
;                 PK4(p0, 0, pa0); PK4(p0, 8, pa1);
;     ...
;                 __builtin_amdgcn_sched_barrier(0);
;                 if (__any(alpha < 1.f)) {
;                     if (hi == 0) al_l[r32] = alpha;
;                     asm volatile("s_waitcnt lgkmcnt(0)" ::: "memory");
;                     float ar[16];
; #pragma unroll
;                     for (int r = 0; r < 16; ++r) ar[r] = al_l[crow(r, hi)];
; #pragma unroll
;                     for (int d = 0; d < 8; ++d)
; #pragma unroll
;                         for (int r = 0; r < 16; ++r) o[d][r] *= ar[r];
;                 }
;                 __builtin_amdgcn_sched_barrier(0);
;                 LAS unsigned char* vbp = ldsl + 65536 + (t & 1) * 32768 + 16384 + v_rd_base(lane);
;                 __builtin_amdgcn_s_setprio(1);
;     ...
;                 {
;                     s16x4 a0, a1, a2, a3, b0_, b1_, b2_, b3_;
;                     PV_RD(0, a0, a1, a2, a3); SB();
;                     PV_RD(1, b0_, b1_, b2_, b3_); SB(); PV_MM(0, a0, a1, a2, a3); SB();
;                     PV_RD(2, a0, a1, a2, a3); SB(); PV_MM(1, b0_, b1_, b2_, b3_); SB();
;                     PV_RD(3, b0_, b1_, b2_, b3_); SB(); PV_MM(2, a0, a1, a2, a3); SB();
;                     PV_RD(4, a0, a1, a2, a3); SB(); PV_MM(3, b0_, b1_, b2_, b3_); SB();
.Lattn_region3:
	ds_read_b64_tr_b16 v[216:217], v212 offset:32768
	ds_read_b64_tr_b16 v[218:219], v212 offset:36864
	ds_read_b64_tr_b16 v[220:221], v212 offset:40960
	ds_read_b64_tr_b16 v[222:223], v212 offset:45056
	ds_read_b64_tr_b16 v[236:237], v212 offset:33280
	ds_read_b64_tr_b16 v[238:239], v212 offset:37376
	ds_read_b64_tr_b16 v[240:241], v212 offset:41472
	ds_read_b64_tr_b16 v[242:243], v212 offset:45568
	v_max3_f32 v226, v140, v141, v142
	v_max3_f32 v226, v226, v143, v144
	v_max3_f32 v226, v226, v145, v146
	v_max3_f32 v226, v226, v147, v148
	v_max3_f32 v226, v226, v149, v150
	v_max3_f32 v226, v226, v151, v152
	v_max3_f32 v226, v226, v153, v154
	v_max_f32_e32 v226, v226, v155
	v_mov_b32_e32 v227, v226
	s_nop 1
	v_permlane32_swap_b32_e32 v226, v227
	v_max_f32_e32 v226, v226, v227
	v_fma_f32 v226, v226, s82, v231
	v_sub_f32_e32 v227, v226, v213
	v_cmp_ge_f32_e32 vcc, s97, v227
	s_cmp_eq_u64 vcc, exec
	v_max_f32_e32 v226, v213, v226
	s_cselect_b64 vcc, -1, 0
	v_sub_f32_e32 v227, v213, v226
	v_cndmask_b32_e32 v213, v226, v213, vcc
	v_sub_f32_e32 v230, v231, v213
	s_waitcnt lgkmcnt(4)
	v_mfma_f32_32x32x16_bf16 v[114:129], v[156:159], v[216:219], v[114:129]
	v_mfma_f32_32x32x16_bf16 v[114:129], v[160:163], v[220:223], v[114:129]
	v_fma_f32 v140, v140, s82, v230
	v_exp_f32_e32 v140, v140
	v_fma_f32 v141, v141, s82, v230
	v_exp_f32_e32 v141, v141
	ds_read_b64_tr_b16 v[216:217], v212 offset:33792
	ds_read_b64_tr_b16 v[218:219], v212 offset:37888
	ds_read_b64_tr_b16 v[220:221], v212 offset:41984
	ds_read_b64_tr_b16 v[222:223], v212 offset:46080
	s_waitcnt lgkmcnt(4)
	v_mfma_f32_32x32x16_bf16 v[98:113], v[156:159], v[236:239], v[98:113]
	v_fma_f32 v142, v142, s82, v230
	v_exp_f32_e32 v142, v142
	v_add_f32_e32 v226, v140, v141
	v_fma_f32 v143, v143, s82, v230
	v_exp_f32_e32 v143, v143
	v_mfma_f32_32x32x16_bf16 v[98:113], v[160:163], v[240:243], v[98:113]
	v_add_f32_e32 v226, v226, v142
	v_fma_f32 v144, v144, s82, v230
	v_exp_f32_e32 v144, v144
	v_add_f32_e32 v226, v226, v143
	v_fma_f32 v145, v145, s82, v230
	ds_read_b64_tr_b16 v[236:237], v212 offset:34304
	ds_read_b64_tr_b16 v[238:239], v212 offset:38400
	ds_read_b64_tr_b16 v[240:241], v212 offset:42496
	ds_read_b64_tr_b16 v[242:243], v212 offset:46592
	s_waitcnt lgkmcnt(4)
	v_mfma_f32_32x32x16_bf16 v[82:97], v[156:159], v[216:219], v[82:97]
	v_exp_f32_e32 v145, v145
	v_add_f32_e32 v226, v226, v144
	v_fma_f32 v146, v146, s82, v230
	v_exp_f32_e32 v146, v146
	v_mfma_f32_32x32x16_bf16 v[82:97], v[160:163], v[220:223], v[82:97]
	v_add_f32_e32 v226, v226, v145
	v_fma_f32 v147, v147, s82, v230
	v_exp_f32_e32 v147, v147
	v_add_f32_e32 v226, v226, v146
	v_fma_f32 v148, v148, s82, v230
	ds_read_b64_tr_b16 v[216:217], v212 offset:34816
	ds_read_b64_tr_b16 v[218:219], v212 offset:38912
	ds_read_b64_tr_b16 v[220:221], v212 offset:43008
	ds_read_b64_tr_b16 v[222:223], v212 offset:47104
	s_waitcnt lgkmcnt(4)
	v_mfma_f32_32x32x16_bf16 v[66:81], v[156:159], v[236:239], v[66:81]
	v_exp_f32_e32 v148, v148
	v_add_f32_e32 v226, v226, v147
	v_fma_f32 v149, v149, s82, v230
	v_exp_f32_e32 v149, v149
	v_mfma_f32_32x32x16_bf16 v[66:81], v[160:163], v[240:243], v[66:81]
	v_add_f32_e32 v226, v226, v148
	v_fma_f32 v150, v150, s82, v230
	v_exp_f32_e32 v150, v150
	v_add_f32_e32 v226, v226, v149
	ds_read_b64_tr_b16 v[236:237], v212 offset:35328
	ds_read_b64_tr_b16 v[238:239], v212 offset:39424
	ds_read_b64_tr_b16 v[240:241], v212 offset:43520
	ds_read_b64_tr_b16 v[242:243], v212 offset:47616
	s_waitcnt lgkmcnt(4)
	v_mfma_f32_32x32x16_bf16 v[50:65], v[156:159], v[216:219], v[50:65]
	v_fma_f32 v151, v151, s82, v230
	v_exp_f32_e32 v151, v151
	v_add_f32_e32 v226, v226, v150
	v_fma_f32 v152, v152, s82, v230
	v_mfma_f32_32x32x16_bf16 v[50:65], v[160:163], v[220:223], v[50:65]
	v_exp_f32_e32 v152, v152
	v_add_f32_e32 v226, v226, v151
	v_fma_f32 v153, v153, s82, v230
	v_exp_f32_e32 v153, v153
	ds_read_b64_tr_b16 v[216:217], v212 offset:35840
	ds_read_b64_tr_b16 v[218:219], v212 offset:39936
	ds_read_b64_tr_b16 v[220:221], v212 offset:44032
	ds_read_b64_tr_b16 v[222:223], v212 offset:48128
	s_waitcnt lgkmcnt(4)
	v_mfma_f32_32x32x16_bf16 v[34:49], v[156:159], v[236:239], v[34:49]
	v_add_f32_e32 v226, v226, v152
	v_fma_f32 v154, v154, s82, v230
	v_exp_f32_e32 v154, v154
	v_add_f32_e32 v226, v226, v153
	v_mfma_f32_32x32x16_bf16 v[34:49], v[160:163], v[240:243], v[34:49]
	v_fma_f32 v155, v155, s82, v230
	v_exp_f32_e32 v155, v155
	v_add_f32_e32 v226, v226, v154
	v_exp_f32_e32 v227, v227
	ds_read_b64_tr_b16 v[236:237], v212 offset:36352
	ds_read_b64_tr_b16 v[238:239], v212 offset:40448
	ds_read_b64_tr_b16 v[240:241], v212 offset:44544
	ds_read_b64_tr_b16 v[242:243], v212 offset:48640
	s_waitcnt lgkmcnt(4)
	v_mfma_f32_32x32x16_bf16 v[18:33], v[156:159], v[216:219], v[18:33]
	v_add_f32_e32 v228, v226, v155
	v_cndmask_b32_e64 v227, v227, 1.0, vcc
	v_mov_b32_e32 v229, v228
	v_cvt_pk_bf16_f32 v132, v140, v141
	v_cvt_pk_bf16_f32 v133, v142, v143
	v_mfma_f32_32x32x16_bf16 v[18:33], v[160:163], v[220:223], v[18:33]
	v_cvt_pk_bf16_f32 v134, v144, v145
	v_cvt_pk_bf16_f32 v135, v146, v147
	v_cvt_pk_bf16_f32 v136, v148, v149
	v_cvt_pk_bf16_f32 v137, v150, v151
	v_cvt_pk_bf16_f32 v138, v152, v153
	s_waitcnt lgkmcnt(0)
	v_mfma_f32_32x32x16_bf16 v[2:17], v[156:159], v[236:239], v[2:17]
	v_cvt_pk_bf16_f32 v139, v154, v155
	v_permlane32_swap_b32_e32 v228, v229
	v_permlane32_swap_b32_e32 v132, v134
	v_permlane32_swap_b32_e32 v133, v135
	v_mfma_f32_32x32x16_bf16 v[2:17], v[160:163], v[240:243], v[2:17]
	v_permlane32_swap_b32_e32 v136, v138
	v_permlane32_swap_b32_e32 v137, v139
	v_add_f32_e32 v228, v228, v229
	v_fma_f32 v130, v130, v227, v228
	s_cbranch_vccz .Lattn_rescale3

; DI int crow(int r, int hi) { return (r & 3) + 8 * (r >> 2) + 4 * hi; }
; DI void phase_attn(int wid0, const Params& p, int L, unsigned char* lds, bool dry) {
;     ...
;                 if (t > 0 && wq0 - (kpos0 + 31) >= 128) {
; #pragma unroll
;                     for (int r = 0; r < 16; ++r) p0[r] = fmaf(p0[r], ATT_C, bfar);
;                 } else {
; #pragma unroll
;                     for (int r = 0; r < 16; ++r) {
;                         const int k0i = crow(r, hi);
;                         const int d0v = qpos - (kpos0 + k0i);
;                         const bool v0 = (d0v >= 0) && (t > 0 || k0i < 16);
;                         const int idx = v0 ? (d0v < 128 ? d0v : 128) : 129;
;                         p0[r] = fmaf(p0[r], ATT_C, tab[idx]);
;                         if ((r & 3) == 3) __builtin_amdgcn_sched_barrier(0);
;                     }
;     ...
;                 if (__any(alpha < 1.f)) {
;                     if (hi == 0) al_l[r32] = alpha;
;                     asm volatile("s_waitcnt lgkmcnt(0)" ::: "memory");
;                     float ar[16];
; #pragma unroll
;                     for (int r = 0; r < 16; ++r) ar[r] = al_l[crow(r, hi)];
; #pragma unroll
;                     for (int d = 0; d < 8; ++d)
; #pragma unroll
;                         for (int r = 0; r < 16; ++r) o[d][r] *= ar[r];
;                 }
.Lattn_near0:
	s_cmp_lg_u32 s67, 1
	s_cbranch_scc0 .Lattn_near_t0
	v_add_u32_e32 v226, s48, v194
	v_sub_u32_e32 v229, v195, v226
	s_mov_b32 s83, 0x20d8c
	v_lshl_add_u32 v226, v229, 2, s83
	ds_read2_b32 v[216:217], v226 offset0:27 offset1:26
	ds_read2_b32 v[218:219], v226 offset0:25 offset1:24
	ds_read2_b32 v[220:221], v226 offset0:19 offset1:18
	ds_read2_b32 v[222:223], v226 offset0:17 offset1:16
	ds_read2_b32 v[236:237], v226 offset0:11 offset1:10
	ds_read2_b32 v[238:239], v226 offset0:9 offset1:8
	ds_read2_b32 v[240:241], v226 offset0:3 offset1:2
	ds_read2_b32 v[242:243], v226 offset0:1 offset1:0
	s_waitcnt lgkmcnt(0)
	v_pk_fma_f32 v[140:141], v[140:141], s[36:37], v[216:217] op_sel_hi:[1,0,1]
	v_pk_fma_f32 v[142:143], v[142:143], s[36:37], v[218:219] op_sel_hi:[1,0,1]
	v_pk_fma_f32 v[144:145], v[144:145], s[36:37], v[220:221] op_sel_hi:[1,0,1]
	v_pk_fma_f32 v[146:147], v[146:147], s[36:37], v[222:223] op_sel_hi:[1,0,1]
	v_pk_fma_f32 v[148:149], v[148:149], s[36:37], v[236:237] op_sel_hi:[1,0,1]
	v_pk_fma_f32 v[150:151], v[150:151], s[36:37], v[238:239] op_sel_hi:[1,0,1]
	v_pk_fma_f32 v[152:153], v[152:153], s[36:37], v[240:241] op_sel_hi:[1,0,1]
	v_pk_fma_f32 v[154:155], v[154:155], s[36:37], v[242:243] op_sel_hi:[1,0,1]
	s_mov_b32 s82, 1.0
	v_mov_b32_e32 v231, 0
	s_branch .Lattn_region0
.Lattn_rescale0:
	s_and_saveexec_b64 s[80:81], s[8:9]
	ds_write_b32 v196, v227 offset:128
	s_or_b64 exec, exec, s[80:81]
	s_waitcnt lgkmcnt(0)
	ds_read_b128 v[152:155], v214 offset:224
	ds_read_b128 v[148:151], v214 offset:192
	ds_read_b128 v[144:147], v214 offset:160
	ds_read_b128 v[140:143], v214 offset:128
	s_waitcnt lgkmcnt(0)
	v_pk_mul_f32 v[126:127], v[126:127], v[152:153]
	v_pk_mul_f32 v[122:123], v[122:123], v[148:149]
	v_pk_mul_f32 v[118:119], v[118:119], v[144:145]
	v_pk_mul_f32 v[128:129], v[128:129], v[154:155]
	v_pk_mul_f32 v[124:125], v[124:125], v[150:151]
	v_pk_mul_f32 v[120:121], v[120:121], v[146:147]
	v_pk_mul_f32 v[116:117], v[116:117], v[142:143]
	v_pk_mul_f32 v[114:115], v[114:115], v[140:141]
	v_pk_mul_f32 v[110:111], v[110:111], v[152:153]
	v_pk_mul_f32 v[106:107], v[106:107], v[148:149]
	v_pk_mul_f32 v[102:103], v[102:103], v[144:145]
	v_pk_mul_f32 v[112:113], v[112:113], v[154:155]
	v_pk_mul_f32 v[108:109], v[108:109], v[150:151]
	v_pk_mul_f32 v[104:105], v[104:105], v[146:147]
	v_pk_mul_f32 v[100:101], v[100:101], v[142:143]
	v_pk_mul_f32 v[98:99], v[98:99], v[140:141]
	v_pk_mul_f32 v[94:95], v[94:95], v[152:153]
	v_pk_mul_f32 v[90:91], v[90:91], v[148:149]
	v_pk_mul_f32 v[86:87], v[86:87], v[144:145]
	v_pk_mul_f32 v[96:97], v[96:97], v[154:155]
	v_pk_mul_f32 v[92:93], v[92:93], v[150:151]
	v_pk_mul_f32 v[88:89], v[88:89], v[146:147]
	v_pk_mul_f32 v[84:85], v[84:85], v[142:143]
	v_pk_mul_f32 v[82:83], v[82:83], v[140:141]
	v_pk_mul_f32 v[78:79], v[78:79], v[152:153]
	v_pk_mul_f32 v[74:75], v[74:75], v[148:149]
	v_pk_mul_f32 v[70:71], v[70:71], v[144:145]
	v_pk_mul_f32 v[80:81], v[80:81], v[154:155]
	v_pk_mul_f32 v[76:77], v[76:77], v[150:151]
	v_pk_mul_f32 v[72:73], v[72:73], v[146:147]
	v_pk_mul_f32 v[68:69], v[68:69], v[142:143]
	v_pk_mul_f32 v[66:67], v[66:67], v[140:141]
	v_pk_mul_f32 v[62:63], v[62:63], v[152:153]
	v_pk_mul_f32 v[58:59], v[58:59], v[148:149]
	v_pk_mul_f32 v[54:55], v[54:55], v[144:145]
	v_pk_mul_f32 v[64:65], v[64:65], v[154:155]
	v_pk_mul_f32 v[60:61], v[60:61], v[150:151]
	v_pk_mul_f32 v[56:57], v[56:57], v[146:147]
	v_pk_mul_f32 v[52:53], v[52:53], v[142:143]
	v_pk_mul_f32 v[50:51], v[50:51], v[140:141]
	v_pk_mul_f32 v[46:47], v[46:47], v[152:153]
	v_pk_mul_f32 v[42:43], v[42:43], v[148:149]
	v_pk_mul_f32 v[38:39], v[38:39], v[144:145]
	v_pk_mul_f32 v[48:49], v[48:49], v[154:155]
	v_pk_mul_f32 v[44:45], v[44:45], v[150:151]
	v_pk_mul_f32 v[40:41], v[40:41], v[146:147]
	v_pk_mul_f32 v[36:37], v[36:37], v[142:143]
	v_pk_mul_f32 v[34:35], v[34:35], v[140:141]
	v_pk_mul_f32 v[30:31], v[30:31], v[152:153]
	v_pk_mul_f32 v[26:27], v[26:27], v[148:149]
	v_pk_mul_f32 v[22:23], v[22:23], v[144:145]
	v_pk_mul_f32 v[32:33], v[32:33], v[154:155]
	v_pk_mul_f32 v[28:29], v[28:29], v[150:151]
	v_pk_mul_f32 v[24:25], v[24:25], v[146:147]
	v_pk_mul_f32 v[20:21], v[20:21], v[142:143]
	v_pk_mul_f32 v[18:19], v[18:19], v[140:141]
	v_pk_mul_f32 v[14:15], v[14:15], v[152:153]
	v_pk_mul_f32 v[10:11], v[10:11], v[148:149]
	v_pk_mul_f32 v[6:7], v[6:7], v[144:145]
	v_pk_mul_f32 v[16:17], v[16:17], v[154:155]
	v_pk_mul_f32 v[12:13], v[12:13], v[150:151]
	v_pk_mul_f32 v[8:9], v[8:9], v[146:147]
	v_pk_mul_f32 v[4:5], v[4:5], v[142:143]
	v_pk_mul_f32 v[2:3], v[2:3], v[140:141]
	s_branch .Lattn_latch0
.Lattn_near1:
	v_add_u32_e32 v226, s48, v194
	v_sub_u32_e32 v229, v195, v226
	s_mov_b32 s83, 0x20d8c
	v_lshl_add_u32 v226, v229, 2, s83
	ds_read2_b32 v[216:217], v226 offset0:27 offset1:26
	ds_read2_b32 v[218:219], v226 offset0:25 offset1:24
	ds_read2_b32 v[220:221], v226 offset0:19 offset1:18
	ds_read2_b32 v[222:223], v226 offset0:17 offset1:16
	ds_read2_b32 v[236:237], v226 offset0:11 offset1:10
	ds_read2_b32 v[238:239], v226 offset0:9 offset1:8
	ds_read2_b32 v[240:241], v226 offset0:3 offset1:2
	ds_read2_b32 v[242:243], v226 offset0:1 offset1:0
	s_waitcnt lgkmcnt(0)
	v_pk_fma_f32 v[140:141], v[140:141], s[36:37], v[216:217] op_sel_hi:[1,0,1]
	v_pk_fma_f32 v[142:143], v[142:143], s[36:37], v[218:219] op_sel_hi:[1,0,1]
	v_pk_fma_f32 v[144:145], v[144:145], s[36:37], v[220:221] op_sel_hi:[1,0,1]
	v_pk_fma_f32 v[146:147], v[146:147], s[36:37], v[222:223] op_sel_hi:[1,0,1]
	v_pk_fma_f32 v[148:149], v[148:149], s[36:37], v[236:237] op_sel_hi:[1,0,1]
	v_pk_fma_f32 v[150:151], v[150:151], s[36:37], v[238:239] op_sel_hi:[1,0,1]
	v_pk_fma_f32 v[152:153], v[152:153], s[36:37], v[240:241] op_sel_hi:[1,0,1]
	v_pk_fma_f32 v[154:155], v[154:155], s[36:37], v[242:243] op_sel_hi:[1,0,1]
	s_mov_b32 s82, 1.0
	v_mov_b32_e32 v231, 0
	s_branch .Lattn_region1

; DI int crow(int r, int hi) { return (r & 3) + 8 * (r >> 2) + 4 * hi; }
; DI void phase_attn(int wid0, const Params& p, int L, unsigned char* lds, bool dry) {
;     ...
;             if (t + 1 < ntiles) attn_stage(kh_ + (size_t)(b * 4096 + 32 * t) * 2048, vh_ + (size_t)(b * 4096 + 32 * t) * 2048, koff, voff, ldsl + 65536 + ((t + 1) & 1) * 32768, wid);
;             const int kpos0 = (t == 0) ? 0 : 16 + 32 * (t - 1);
;             if (kpos0 <= wq0 + 31) {
;     ...
;                 } else {
; #pragma unroll
;                     for (int r = 0; r < 16; ++r) {
;                         const int k0i = crow(r, hi);
;                         const int d0v = qpos - (kpos0 + k0i);
;                         const bool v0 = (d0v >= 0) && (t > 0 || k0i < 16);
;                         const int idx = v0 ? (d0v < 128 ? d0v : 128) : 129;
;                         p0[r] = fmaf(p0[r], ATT_C, tab[idx]);
;                         if ((r & 3) == 3) __builtin_amdgcn_sched_barrier(0);
;                     }
.Lattn_near_t0:
	s_cmp_lg_u32 s67, 1
	s_cselect_b64 s[80:81], -1, 0
	v_add_u32_e32 v226, s48, v194
	v_sub_u32_e32 v229, v195, v226
	v_sub_u32_e32 v216, v195, v226
	v_cmp_lt_i32_e32 vcc, -1, v216
	s_or_b64 s[82:83], s[10:11], s[80:81]
	v_add_u32_e32 v217, s48, v197
	v_min_i32_e32 v216, 0x80, v216
	s_and_b64 vcc, s[82:83], vcc
	v_sub_u32_e32 v217, v195, v217
	v_cndmask_b32_e32 v216, v187, v216, vcc
	v_cmp_lt_i32_e32 vcc, -1, v217
	s_or_b64 s[82:83], s[12:13], s[80:81]
	v_add_u32_e32 v218, s48, v198
	v_min_i32_e32 v217, 0x80, v217
	s_and_b64 vcc, s[82:83], vcc
	v_sub_u32_e32 v218, v195, v218
	v_cndmask_b32_e32 v217, v187, v217, vcc
	v_cmp_lt_i32_e32 vcc, -1, v218
	s_or_b64 s[82:83], s[14:15], s[80:81]
	v_add_u32_e32 v219, s48, v199
	v_min_i32_e32 v218, 0x80, v218
	s_and_b64 vcc, s[82:83], vcc
	v_sub_u32_e32 v219, v195, v219
	v_cndmask_b32_e32 v218, v187, v218, vcc
	v_cmp_lt_i32_e32 vcc, -1, v219
	s_or_b64 s[82:83], s[16:17], s[80:81]
	v_min_i32_e32 v219, 0x80, v219
	s_and_b64 vcc, s[82:83], vcc
	v_cndmask_b32_e32 v219, v187, v219, vcc
	v_lshl_add_u32 v216, v216, 2, s37
	v_lshl_add_u32 v217, v217, 2, s37
	v_lshl_add_u32 v218, v218, 2, s37
	v_lshl_add_u32 v219, v219, 2, s37
	ds_read_b32 v216, v216
	ds_read_b32 v217, v217
	ds_read_b32 v218, v218
	ds_read_b32 v219, v219
	v_add_u32_e32 v220, -8, v229
	v_cmp_lt_i32_e32 vcc, -1, v220
	s_or_b64 s[82:83], s[18:19], s[80:81]
	v_min_i32_e32 v220, 0x80, v220
	s_and_b64 vcc, s[82:83], vcc
	v_add_u32_e32 v221, -9, v229
	v_cndmask_b32_e32 v220, v187, v220, vcc
	v_cmp_lt_i32_e32 vcc, -1, v221
	v_min_i32_e32 v221, 0x80, v221
	s_and_b64 vcc, s[82:83], vcc
	v_add_u32_e32 v222, -10, v229
	v_cndmask_b32_e32 v221, v187, v221, vcc
	v_cmp_lt_i32_e32 vcc, -1, v222
	v_min_i32_e32 v222, 0x80, v222
	s_and_b64 vcc, s[82:83], vcc
	v_add_u32_e32 v223, -11, v229
	v_cndmask_b32_e32 v222, v187, v222, vcc
	v_cmp_lt_i32_e32 vcc, -1, v223
	v_min_i32_e32 v223, 0x80, v223
	s_and_b64 vcc, s[82:83], vcc
	v_cndmask_b32_e32 v223, v187, v223, vcc
	v_lshl_add_u32 v220, v220, 2, s37
	v_lshl_add_u32 v221, v221, 2, s37
	v_lshl_add_u32 v222, v222, 2, s37
	v_lshl_add_u32 v223, v223, 2, s37
	ds_read_b32 v220, v220
	ds_read_b32 v221, v221
	ds_read_b32 v222, v222
	ds_read_b32 v223, v223
	v_add_u32_e32 v236, -16, v229
	v_cmp_lt_i32_e32 vcc, -1, v236
	s_or_b64 s[82:83], s[20:21], s[80:81]
	v_min_i32_e32 v236, 0x80, v236
	s_and_b64 vcc, s[82:83], vcc
	v_add_u32_e32 v237, 0xffffffef, v229
	v_cndmask_b32_e32 v236, v187, v236, vcc
	v_cmp_lt_i32_e32 vcc, -1, v237
	v_min_i32_e32 v237, 0x80, v237
	s_and_b64 vcc, s[82:83], vcc
	v_add_u32_e32 v238, 0xffffffee, v229
	v_cndmask_b32_e32 v237, v187, v237, vcc
	v_cmp_lt_i32_e32 vcc, -1, v238
	v_min_i32_e32 v238, 0x80, v238
	s_and_b64 vcc, s[82:83], vcc
	v_add_u32_e32 v239, 0xffffffed, v229
	v_cndmask_b32_e32 v238, v187, v238, vcc
	v_cmp_lt_i32_e32 vcc, -1, v239
	v_min_i32_e32 v239, 0x80, v239
	s_and_b64 vcc, s[82:83], vcc
	v_cndmask_b32_e32 v239, v187, v239, vcc
	v_lshl_add_u32 v236, v236, 2, s37
	v_lshl_add_u32 v237, v237, 2, s37
	v_lshl_add_u32 v238, v238, 2, s37
	v_lshl_add_u32 v239, v239, 2, s37
	ds_read_b32 v236, v236
	ds_read_b32 v237, v237
	ds_read_b32 v238, v238
	ds_read_b32 v239, v239
	v_add_u32_e32 v240, 0xffffffe8, v229
	v_cmp_lt_i32_e32 vcc, -1, v240
	s_or_b64 s[80:81], s[22:23], s[80:81]
	v_min_i32_e32 v240, 0x80, v240
	s_and_b64 vcc, s[80:81], vcc
	v_add_u32_e32 v241, 0xffffffe7, v229
	v_cndmask_b32_e32 v240, v187, v240, vcc
	v_cmp_lt_i32_e32 vcc, -1, v241
	v_min_i32_e32 v241, 0x80, v241
	s_and_b64 vcc, s[80:81], vcc
	v_add_u32_e32 v242, 0xffffffe6, v229
	v_cndmask_b32_e32 v241, v187, v241, vcc
	v_cmp_lt_i32_e32 vcc, -1, v242
	v_min_i32_e32 v242, 0x80, v242
	s_and_b64 vcc, s[80:81], vcc
	v_add_u32_e32 v226, 0xffffffe5, v229
	v_cndmask_b32_e32 v242, v187, v242, vcc
	v_cmp_lt_i32_e32 vcc, -1, v226
	v_min_i32_e32 v226, 0x80, v226
	s_and_b64 vcc, s[80:81], vcc
	v_lshl_add_u32 v240, v240, 2, s37
	v_lshl_add_u32 v241, v241, 2, s37
	v_lshl_add_u32 v242, v242, 2, s37
	v_cndmask_b32_e32 v226, v187, v226, vcc
	v_lshl_add_u32 v226, v226, 2, s37
	ds_read_b32 v240, v240
	ds_read_b32 v241, v241
	ds_read_b32 v242, v242
	ds_read_b32 v243, v226
	s_waitcnt lgkmcnt(0)
	v_pk_fma_f32 v[140:141], v[140:141], s[36:37], v[216:217] op_sel_hi:[1,0,1]
	v_pk_fma_f32 v[142:143], v[142:143], s[36:37], v[218:219] op_sel_hi:[1,0,1]
	v_pk_fma_f32 v[144:145], v[144:145], s[36:37], v[220:221] op_sel_hi:[1,0,1]
	v_pk_fma_f32 v[146:147], v[146:147], s[36:37], v[222:223] op_sel_hi:[1,0,1]
	v_pk_fma_f32 v[148:149], v[148:149], s[36:37], v[236:237] op_sel_hi:[1,0,1]
	v_pk_fma_f32 v[150:151], v[150:151], s[36:37], v[238:239] op_sel_hi:[1,0,1]
	v_pk_fma_f32 v[152:153], v[152:153], s[36:37], v[240:241] op_sel_hi:[1,0,1]
	v_pk_fma_f32 v[154:155], v[154:155], s[36:37], v[242:243] op_sel_hi:[1,0,1]
	s_mov_b32 s82, 1.0
	v_mov_b32_e32 v231, 0
	s_branch .Lattn_region0
.Lattn_skip0:
	s_add_i32 m0, s4, 0x8000
	s_nop 0
	global_load_lds_dwordx4 v131, s[88:89]
	s_add_i32 m0, s4, 0xa000
	s_nop 0
	global_load_lds_dwordx4 v131, s[90:91]
	v_add_u32_e32 v131, 0x20000, v131
	s_add_i32 m0, s96, 0x4000
	s_nop 0
	global_load_lds_dwordx4 v208, s[92:93]
	s_add_i32 m0, s96, 0x6000
	s_nop 0
	global_load_lds_dwordx4 v208, s[94:95]
	v_add_u32_e32 v208, 0x20000, v208
	s_bitcmp1_b32 s100, 8
	s_cbranch_scc0 .Lattn_latch0
